# VM8: pair-tile GEMM k-loops wait only for the previous half-step's A-tile DMA pieces (vmcnt 8) - its two B pieces belong to a later k-tile and may stay in flight
# speedup vs baseline: 1.0049x; 1.0049x over previous
.Lg1_loop:
	ds_read_b128 v[92:95], v84 offset:0
	ds_read_b128 v[96:99], v84 offset:4096
	ds_read_b128 v[188:191], v85 offset:0
	ds_read_b128 v[192:195], v85 offset:4096
	ds_read_b128 v[100:103], v86 offset:0
	ds_read_b128 v[144:147], v86 offset:4096
	ds_read_b128 v[212:215], v87 offset:0
	ds_read_b128 v[216:219], v87 offset:4096
	ds_read_b128 v[148:151], v88 offset:0
	ds_read_b128 v[152:155], v88 offset:4096
	ds_read_b128 v[220:223], v89 offset:0
	ds_read_b128 v[224:227], v89 offset:4096
	ds_read_b128 v[180:183], v90 offset:0
	ds_read_b128 v[184:187], v90 offset:4096
	ds_read_b128 v[228:231], v91 offset:0
	ds_read_b128 v[252:255], v91 offset:4096
	s_waitcnt lgkmcnt(0)
	s_barrier
	s_mov_b32 m0, s1
	v_mfma_f32_32x32x16_bf16 v[18:33], v[92:95], v[188:191], v[18:33]
	global_load_lds_dwordx4 v[66:67], off
	v_mfma_f32_32x32x16_bf16 v[50:65], v[92:95], v[192:195], v[50:65]
	v_mfma_f32_32x32x16_bf16 v[2:17], v[96:99], v[188:191], v[2:17]
	s_add_i32 m0, s1, 0x400
	v_mfma_f32_32x32x16_bf16 v[34:49], v[96:99], v[192:195], v[34:49]
	global_load_lds_dwordx4 v[70:71], off
	v_mfma_f32_32x32x16_bf16 v[18:33], v[100:103], v[212:215], v[18:33]
	s_add_i32 m0, s1, 0x800
	v_mfma_f32_32x32x16_bf16 v[50:65], v[100:103], v[216:219], v[50:65]
	global_load_lds_dwordx4 v[74:75], off
	v_mfma_f32_32x32x16_bf16 v[2:17], v[144:147], v[212:215], v[2:17]
	v_mfma_f32_32x32x16_bf16 v[34:49], v[144:147], v[216:219], v[34:49]
	s_add_i32 m0, s1, 0xc00
	v_mfma_f32_32x32x16_bf16 v[18:33], v[148:151], v[220:223], v[18:33]
	global_load_lds_dwordx4 v[78:79], off
	v_mfma_f32_32x32x16_bf16 v[50:65], v[148:151], v[224:227], v[50:65]
	v_mfma_f32_32x32x16_bf16 v[2:17], v[152:155], v[220:223], v[2:17]
	s_mov_b32 m0, s8
	v_mfma_f32_32x32x16_bf16 v[34:49], v[152:155], v[224:227], v[34:49]
	global_load_lds_dwordx4 v[68:69], off
	v_lshl_add_u64 v[68:69], v[68:69], 0, s[34:35]
	v_mfma_f32_32x32x16_bf16 v[18:33], v[180:183], v[228:231], v[18:33]
	s_mov_b32 m0, s9
	v_mfma_f32_32x32x16_bf16 v[50:65], v[180:183], v[252:255], v[50:65]
	global_load_lds_dwordx4 v[72:73], off
	v_lshl_add_u64 v[72:73], v[72:73], 0, s[34:35]
	v_mfma_f32_32x32x16_bf16 v[2:17], v[184:187], v[228:231], v[2:17]
	v_mfma_f32_32x32x16_bf16 v[34:49], v[184:187], v[252:255], v[34:49]
	s_waitcnt vmcnt(8)
	s_barrier
	ds_read_b128 v[92:95], v84 offset:32768
	ds_read_b128 v[96:99], v84 offset:36864
	ds_read_b128 v[100:103], v86 offset:32768
	ds_read_b128 v[144:147], v86 offset:36864
	ds_read_b128 v[148:151], v88 offset:32768
	ds_read_b128 v[152:155], v88 offset:36864
	ds_read_b128 v[180:183], v90 offset:32768
	ds_read_b128 v[184:187], v90 offset:36864
	s_waitcnt lgkmcnt(0)
	s_barrier
	s_mov_b32 m0, s6
	v_lshl_add_u64 v[82:83], v[66:67], 0, s[26:27]
	v_mfma_f32_32x32x16_bf16 v[104:119], v[92:95], v[188:191], v[104:119]
	global_load_lds_dwordx4 v[82:83], off
	v_lshl_add_u64 v[66:67], v[66:67], 0, s[34:35]
	v_mfma_f32_32x32x16_bf16 v[128:143], v[92:95], v[192:195], v[128:143]
	v_mfma_f32_32x32x16_bf16 v[196:211], v[96:99], v[188:191], v[196:211]
	s_mov_b32 m0, s13
	v_lshl_add_u64 v[82:83], v[70:71], 0, s[26:27]
	v_mfma_f32_32x32x16_bf16 v[236:251], v[96:99], v[192:195], v[236:251]
	global_load_lds_dwordx4 v[82:83], off
	v_lshl_add_u64 v[70:71], v[70:71], 0, s[34:35]
	v_mfma_f32_32x32x16_bf16 v[104:119], v[100:103], v[212:215], v[104:119]
	s_mov_b32 m0, s15
	v_lshl_add_u64 v[82:83], v[74:75], 0, s[26:27]
	v_mfma_f32_32x32x16_bf16 v[128:143], v[100:103], v[216:219], v[128:143]
	global_load_lds_dwordx4 v[82:83], off
	v_lshl_add_u64 v[74:75], v[74:75], 0, s[34:35]
	v_mfma_f32_32x32x16_bf16 v[196:211], v[144:147], v[212:215], v[196:211]
	v_mfma_f32_32x32x16_bf16 v[236:251], v[144:147], v[216:219], v[236:251]
	s_mov_b32 m0, s17
	v_lshl_add_u64 v[82:83], v[78:79], 0, s[26:27]
	v_mfma_f32_32x32x16_bf16 v[104:119], v[148:151], v[220:223], v[104:119]
	global_load_lds_dwordx4 v[82:83], off
	v_lshl_add_u64 v[78:79], v[78:79], 0, s[34:35]
	v_mfma_f32_32x32x16_bf16 v[128:143], v[148:151], v[224:227], v[128:143]
	v_mfma_f32_32x32x16_bf16 v[196:211], v[152:155], v[220:223], v[196:211]
	s_mov_b32 m0, s10
	v_mfma_f32_32x32x16_bf16 v[236:251], v[152:155], v[224:227], v[236:251]
	global_load_lds_dwordx4 v[76:77], off
	v_lshl_add_u64 v[76:77], v[76:77], 0, s[34:35]
	v_mfma_f32_32x32x16_bf16 v[104:119], v[180:183], v[228:231], v[104:119]
	s_mov_b32 m0, s11
	v_mfma_f32_32x32x16_bf16 v[128:143], v[180:183], v[252:255], v[128:143]
	global_load_lds_dwordx4 v[80:81], off
	v_lshl_add_u64 v[80:81], v[80:81], 0, s[34:35]
	v_mfma_f32_32x32x16_bf16 v[196:211], v[184:187], v[228:231], v[196:211]
	v_mfma_f32_32x32x16_bf16 v[236:251], v[184:187], v[252:255], v[236:251]
	s_waitcnt vmcnt(8)
	s_barrier
	ds_read_b128 v[92:95], v84 offset:0
	ds_read_b128 v[96:99], v84 offset:4096
	ds_read_b128 v[188:191], v85 offset:32768
	ds_read_b128 v[192:195], v85 offset:36864
	ds_read_b128 v[100:103], v86 offset:0
	ds_read_b128 v[144:147], v86 offset:4096
	ds_read_b128 v[212:215], v87 offset:32768
	ds_read_b128 v[216:219], v87 offset:36864
	ds_read_b128 v[148:151], v88 offset:0
	ds_read_b128 v[152:155], v88 offset:4096
	ds_read_b128 v[220:223], v89 offset:32768
	ds_read_b128 v[224:227], v89 offset:36864
	ds_read_b128 v[180:183], v90 offset:0
	ds_read_b128 v[184:187], v90 offset:4096
	ds_read_b128 v[228:231], v91 offset:32768
	ds_read_b128 v[252:255], v91 offset:36864
	s_waitcnt lgkmcnt(0)
	s_barrier
	s_mov_b32 m0, s1
	v_mfma_f32_32x32x16_bf16 v[18:33], v[92:95], v[188:191], v[18:33]
	global_load_lds_dwordx4 v[66:67], off
	v_mfma_f32_32x32x16_bf16 v[50:65], v[92:95], v[192:195], v[50:65]
	v_mfma_f32_32x32x16_bf16 v[2:17], v[96:99], v[188:191], v[2:17]
	s_add_i32 m0, s1, 0x400
	v_mfma_f32_32x32x16_bf16 v[34:49], v[96:99], v[192:195], v[34:49]
	global_load_lds_dwordx4 v[70:71], off
	v_mfma_f32_32x32x16_bf16 v[18:33], v[100:103], v[212:215], v[18:33]
	s_add_i32 m0, s1, 0x800
	v_mfma_f32_32x32x16_bf16 v[50:65], v[100:103], v[216:219], v[50:65]
	global_load_lds_dwordx4 v[74:75], off
	v_mfma_f32_32x32x16_bf16 v[2:17], v[144:147], v[212:215], v[2:17]
	v_mfma_f32_32x32x16_bf16 v[34:49], v[144:147], v[216:219], v[34:49]
	s_add_i32 m0, s1, 0xc00
	v_mfma_f32_32x32x16_bf16 v[18:33], v[148:151], v[220:223], v[18:33]
	global_load_lds_dwordx4 v[78:79], off
	v_mfma_f32_32x32x16_bf16 v[50:65], v[148:151], v[224:227], v[50:65]
	v_mfma_f32_32x32x16_bf16 v[2:17], v[152:155], v[220:223], v[2:17]
	s_mov_b32 m0, s7
	v_mfma_f32_32x32x16_bf16 v[34:49], v[152:155], v[224:227], v[34:49]
	global_load_lds_dwordx4 v[68:69], off
	v_lshl_add_u64 v[68:69], v[68:69], 0, s[34:35]
	v_mfma_f32_32x32x16_bf16 v[18:33], v[180:183], v[228:231], v[18:33]
	s_mov_b32 m0, s14
	v_mfma_f32_32x32x16_bf16 v[50:65], v[180:183], v[252:255], v[50:65]
	global_load_lds_dwordx4 v[72:73], off
	v_lshl_add_u64 v[72:73], v[72:73], 0, s[34:35]
	v_mfma_f32_32x32x16_bf16 v[2:17], v[184:187], v[228:231], v[2:17]
	v_mfma_f32_32x32x16_bf16 v[34:49], v[184:187], v[252:255], v[34:49]
	s_waitcnt vmcnt(8)
	s_barrier
	ds_read_b128 v[92:95], v84 offset:32768
	ds_read_b128 v[96:99], v84 offset:36864
	ds_read_b128 v[100:103], v86 offset:32768
	ds_read_b128 v[144:147], v86 offset:36864
	ds_read_b128 v[148:151], v88 offset:32768
	ds_read_b128 v[152:155], v88 offset:36864
	ds_read_b128 v[180:183], v90 offset:32768
	ds_read_b128 v[184:187], v90 offset:36864
	s_waitcnt lgkmcnt(0)
	s_barrier
	s_mov_b32 m0, s6
	v_lshl_add_u64 v[82:83], v[66:67], 0, s[26:27]
	v_mfma_f32_32x32x16_bf16 v[104:119], v[92:95], v[188:191], v[104:119]
	global_load_lds_dwordx4 v[82:83], off
	v_lshl_add_u64 v[66:67], v[66:67], 0, s[34:35]
	v_mfma_f32_32x32x16_bf16 v[128:143], v[92:95], v[192:195], v[128:143]
	v_mfma_f32_32x32x16_bf16 v[196:211], v[96:99], v[188:191], v[196:211]
	s_mov_b32 m0, s13
	v_lshl_add_u64 v[82:83], v[70:71], 0, s[26:27]
	v_mfma_f32_32x32x16_bf16 v[236:251], v[96:99], v[192:195], v[236:251]
	global_load_lds_dwordx4 v[82:83], off
	v_lshl_add_u64 v[70:71], v[70:71], 0, s[34:35]
	v_mfma_f32_32x32x16_bf16 v[104:119], v[100:103], v[212:215], v[104:119]
	s_mov_b32 m0, s15
	v_lshl_add_u64 v[82:83], v[74:75], 0, s[26:27]
	v_mfma_f32_32x32x16_bf16 v[128:143], v[100:103], v[216:219], v[128:143]
	global_load_lds_dwordx4 v[82:83], off
	v_lshl_add_u64 v[74:75], v[74:75], 0, s[34:35]
	v_mfma_f32_32x32x16_bf16 v[196:211], v[144:147], v[212:215], v[196:211]
	v_mfma_f32_32x32x16_bf16 v[236:251], v[144:147], v[216:219], v[236:251]
	s_mov_b32 m0, s17
	v_lshl_add_u64 v[82:83], v[78:79], 0, s[26:27]
	v_mfma_f32_32x32x16_bf16 v[104:119], v[148:151], v[220:223], v[104:119]
	global_load_lds_dwordx4 v[82:83], off
	v_lshl_add_u64 v[78:79], v[78:79], 0, s[34:35]
	v_mfma_f32_32x32x16_bf16 v[128:143], v[148:151], v[224:227], v[128:143]
	v_mfma_f32_32x32x16_bf16 v[196:211], v[152:155], v[220:223], v[196:211]
	s_mov_b32 m0, s16
	v_mfma_f32_32x32x16_bf16 v[236:251], v[152:155], v[224:227], v[236:251]
	global_load_lds_dwordx4 v[76:77], off
	v_lshl_add_u64 v[76:77], v[76:77], 0, s[34:35]
	v_mfma_f32_32x32x16_bf16 v[104:119], v[180:183], v[228:231], v[104:119]
	s_mov_b32 m0, s25
	v_mfma_f32_32x32x16_bf16 v[128:143], v[180:183], v[252:255], v[128:143]
	global_load_lds_dwordx4 v[80:81], off
	v_lshl_add_u64 v[80:81], v[80:81], 0, s[34:35]
	v_mfma_f32_32x32x16_bf16 v[196:211], v[184:187], v[228:231], v[196:211]
	v_mfma_f32_32x32x16_bf16 v[236:251], v[184:187], v[252:255], v[236:251]
	s_waitcnt vmcnt(8)
	s_barrier
	s_add_i32 s12, s12, 2
	s_cmp_lt_u32 s12, 14
	s_cbranch_scc1 .Lg1_loop
	ds_read_b128 v[92:95], v84 offset:0
	ds_read_b128 v[96:99], v84 offset:4096
	ds_read_b128 v[188:191], v85 offset:0
	ds_read_b128 v[192:195], v85 offset:4096
	ds_read_b128 v[100:103], v86 offset:0
	ds_read_b128 v[144:147], v86 offset:4096
	ds_read_b128 v[212:215], v87 offset:0
	ds_read_b128 v[216:219], v87 offset:4096
	ds_read_b128 v[148:151], v88 offset:0
	ds_read_b128 v[152:155], v88 offset:4096
	ds_read_b128 v[220:223], v89 offset:0
	ds_read_b128 v[224:227], v89 offset:4096
	ds_read_b128 v[180:183], v90 offset:0
	ds_read_b128 v[184:187], v90 offset:4096
	ds_read_b128 v[228:231], v91 offset:0
	ds_read_b128 v[252:255], v91 offset:4096
	s_waitcnt lgkmcnt(0)
	s_barrier
	s_mov_b32 m0, s1
	v_mfma_f32_32x32x16_bf16 v[18:33], v[92:95], v[188:191], v[18:33]
	global_load_lds_dwordx4 v[66:67], off
	v_mfma_f32_32x32x16_bf16 v[50:65], v[92:95], v[192:195], v[50:65]
	v_mfma_f32_32x32x16_bf16 v[2:17], v[96:99], v[188:191], v[2:17]
	s_add_i32 m0, s1, 0x400
	v_mfma_f32_32x32x16_bf16 v[34:49], v[96:99], v[192:195], v[34:49]
	global_load_lds_dwordx4 v[70:71], off
	v_mfma_f32_32x32x16_bf16 v[18:33], v[100:103], v[212:215], v[18:33]
	v_mfma_f32_32x32x16_bf16 v[50:65], v[100:103], v[216:219], v[50:65]
	v_mfma_f32_32x32x16_bf16 v[2:17], v[144:147], v[212:215], v[2:17]
	v_mfma_f32_32x32x16_bf16 v[34:49], v[144:147], v[216:219], v[34:49]
	s_add_i32 m0, s1, 0x800
	v_mfma_f32_32x32x16_bf16 v[18:33], v[148:151], v[220:223], v[18:33]
	global_load_lds_dwordx4 v[74:75], off
	v_mfma_f32_32x32x16_bf16 v[50:65], v[148:151], v[224:227], v[50:65]
	v_mfma_f32_32x32x16_bf16 v[2:17], v[152:155], v[220:223], v[2:17]
	s_add_i32 m0, s1, 0xc00
	v_mfma_f32_32x32x16_bf16 v[34:49], v[152:155], v[224:227], v[34:49]
	global_load_lds_dwordx4 v[78:79], off
	v_mfma_f32_32x32x16_bf16 v[18:33], v[180:183], v[228:231], v[18:33]
	v_mfma_f32_32x32x16_bf16 v[50:65], v[180:183], v[252:255], v[50:65]
	v_mfma_f32_32x32x16_bf16 v[2:17], v[184:187], v[228:231], v[2:17]
	v_mfma_f32_32x32x16_bf16 v[34:49], v[184:187], v[252:255], v[34:49]
	s_waitcnt vmcnt(4)
	s_barrier
	ds_read_b128 v[92:95], v84 offset:32768
	ds_read_b128 v[96:99], v84 offset:36864
	ds_read_b128 v[100:103], v86 offset:32768
	ds_read_b128 v[144:147], v86 offset:36864
	ds_read_b128 v[148:151], v88 offset:32768
	ds_read_b128 v[152:155], v88 offset:36864
	ds_read_b128 v[180:183], v90 offset:32768
	ds_read_b128 v[184:187], v90 offset:36864
	s_waitcnt lgkmcnt(0)
	s_barrier
	s_mov_b32 m0, s6
	v_lshl_add_u64 v[82:83], v[66:67], 0, s[26:27]
	v_mfma_f32_32x32x16_bf16 v[104:119], v[92:95], v[188:191], v[104:119]
	global_load_lds_dwordx4 v[82:83], off
	v_lshl_add_u64 v[66:67], v[66:67], 0, s[34:35]
	v_mfma_f32_32x32x16_bf16 v[128:143], v[92:95], v[192:195], v[128:143]
	v_mfma_f32_32x32x16_bf16 v[196:211], v[96:99], v[188:191], v[196:211]
	s_mov_b32 m0, s13
	v_lshl_add_u64 v[82:83], v[70:71], 0, s[26:27]
	v_mfma_f32_32x32x16_bf16 v[236:251], v[96:99], v[192:195], v[236:251]
	global_load_lds_dwordx4 v[82:83], off
	v_lshl_add_u64 v[70:71], v[70:71], 0, s[34:35]
	v_mfma_f32_32x32x16_bf16 v[104:119], v[100:103], v[212:215], v[104:119]
	v_mfma_f32_32x32x16_bf16 v[128:143], v[100:103], v[216:219], v[128:143]
	v_mfma_f32_32x32x16_bf16 v[196:211], v[144:147], v[212:215], v[196:211]
	v_mfma_f32_32x32x16_bf16 v[236:251], v[144:147], v[216:219], v[236:251]
	s_mov_b32 m0, s15
	v_lshl_add_u64 v[82:83], v[74:75], 0, s[26:27]
	v_mfma_f32_32x32x16_bf16 v[104:119], v[148:151], v[220:223], v[104:119]
	global_load_lds_dwordx4 v[82:83], off
	v_lshl_add_u64 v[74:75], v[74:75], 0, s[34:35]
	v_mfma_f32_32x32x16_bf16 v[128:143], v[148:151], v[224:227], v[128:143]
	v_mfma_f32_32x32x16_bf16 v[196:211], v[152:155], v[220:223], v[196:211]
	s_mov_b32 m0, s17
	v_lshl_add_u64 v[82:83], v[78:79], 0, s[26:27]
	v_mfma_f32_32x32x16_bf16 v[236:251], v[152:155], v[224:227], v[236:251]
	global_load_lds_dwordx4 v[82:83], off
	v_lshl_add_u64 v[78:79], v[78:79], 0, s[34:35]
	v_mfma_f32_32x32x16_bf16 v[104:119], v[180:183], v[228:231], v[104:119]
	v_mfma_f32_32x32x16_bf16 v[128:143], v[180:183], v[252:255], v[128:143]
	v_mfma_f32_32x32x16_bf16 v[196:211], v[184:187], v[228:231], v[196:211]
	v_mfma_f32_32x32x16_bf16 v[236:251], v[184:187], v[252:255], v[236:251]
	s_waitcnt vmcnt(4)
	s_barrier
	ds_read_b128 v[92:95], v84 offset:0
	ds_read_b128 v[96:99], v84 offset:4096
	ds_read_b128 v[188:191], v85 offset:32768
	ds_read_b128 v[192:195], v85 offset:36864
	ds_read_b128 v[100:103], v86 offset:0
	ds_read_b128 v[144:147], v86 offset:4096
	ds_read_b128 v[212:215], v87 offset:32768
	ds_read_b128 v[216:219], v87 offset:36864
	ds_read_b128 v[148:151], v88 offset:0
	ds_read_b128 v[152:155], v88 offset:4096
	ds_read_b128 v[220:223], v89 offset:32768
	ds_read_b128 v[224:227], v89 offset:36864
	ds_read_b128 v[180:183], v90 offset:0
	ds_read_b128 v[184:187], v90 offset:4096
	ds_read_b128 v[228:231], v91 offset:32768
	ds_read_b128 v[252:255], v91 offset:36864
	s_waitcnt lgkmcnt(0)
	s_barrier
	v_mfma_f32_32x32x16_bf16 v[18:33], v[92:95], v[188:191], v[18:33]
	v_mfma_f32_32x32x16_bf16 v[50:65], v[92:95], v[192:195], v[50:65]
	v_mfma_f32_32x32x16_bf16 v[2:17], v[96:99], v[188:191], v[2:17]
	v_mfma_f32_32x32x16_bf16 v[34:49], v[96:99], v[192:195], v[34:49]
	v_mfma_f32_32x32x16_bf16 v[18:33], v[100:103], v[212:215], v[18:33]
	v_mfma_f32_32x32x16_bf16 v[50:65], v[100:103], v[216:219], v[50:65]
	v_mfma_f32_32x32x16_bf16 v[2:17], v[144:147], v[212:215], v[2:17]
	v_mfma_f32_32x32x16_bf16 v[34:49], v[144:147], v[216:219], v[34:49]
	v_mfma_f32_32x32x16_bf16 v[18:33], v[148:151], v[220:223], v[18:33]
	v_mfma_f32_32x32x16_bf16 v[50:65], v[148:151], v[224:227], v[50:65]
	v_mfma_f32_32x32x16_bf16 v[2:17], v[152:155], v[220:223], v[2:17]
	v_mfma_f32_32x32x16_bf16 v[34:49], v[152:155], v[224:227], v[34:49]
	v_mfma_f32_32x32x16_bf16 v[18:33], v[180:183], v[228:231], v[18:33]
	v_mfma_f32_32x32x16_bf16 v[50:65], v[180:183], v[252:255], v[50:65]
	v_mfma_f32_32x32x16_bf16 v[2:17], v[184:187], v[228:231], v[2:17]
	v_mfma_f32_32x32x16_bf16 v[34:49], v[184:187], v[252:255], v[34:49]
	s_waitcnt vmcnt(0)
	s_barrier
	ds_read_b128 v[92:95], v84 offset:32768
	ds_read_b128 v[96:99], v84 offset:36864
	ds_read_b128 v[100:103], v86 offset:32768
	ds_read_b128 v[144:147], v86 offset:36864
	ds_read_b128 v[148:151], v88 offset:32768
	ds_read_b128 v[152:155], v88 offset:36864
	ds_read_b128 v[180:183], v90 offset:32768
	ds_read_b128 v[184:187], v90 offset:36864
	s_waitcnt lgkmcnt(0)
	s_barrier
	v_mfma_f32_32x32x16_bf16 v[104:119], v[92:95], v[188:191], v[104:119]
	v_mfma_f32_32x32x16_bf16 v[128:143], v[92:95], v[192:195], v[128:143]
	v_mfma_f32_32x32x16_bf16 v[196:211], v[96:99], v[188:191], v[196:211]
	v_mfma_f32_32x32x16_bf16 v[236:251], v[96:99], v[192:195], v[236:251]
	v_mfma_f32_32x32x16_bf16 v[104:119], v[100:103], v[212:215], v[104:119]
	v_mfma_f32_32x32x16_bf16 v[128:143], v[100:103], v[216:219], v[128:143]
	v_mfma_f32_32x32x16_bf16 v[196:211], v[144:147], v[212:215], v[196:211]
	v_mfma_f32_32x32x16_bf16 v[236:251], v[144:147], v[216:219], v[236:251]
	v_mfma_f32_32x32x16_bf16 v[104:119], v[148:151], v[220:223], v[104:119]
	v_mfma_f32_32x32x16_bf16 v[128:143], v[148:151], v[224:227], v[128:143]
	v_mfma_f32_32x32x16_bf16 v[196:211], v[152:155], v[220:223], v[196:211]
	v_mfma_f32_32x32x16_bf16 v[236:251], v[152:155], v[224:227], v[236:251]
	v_mfma_f32_32x32x16_bf16 v[104:119], v[180:183], v[228:231], v[104:119]
	v_mfma_f32_32x32x16_bf16 v[128:143], v[180:183], v[252:255], v[128:143]
	v_mfma_f32_32x32x16_bf16 v[196:211], v[184:187], v[228:231], v[196:211]
	v_mfma_f32_32x32x16_bf16 v[236:251], v[184:187], v[252:255], v[236:251]
	s_waitcnt vmcnt(0) lgkmcnt(0)
	s_barrier
	s_branch .LBB0_187
.Lg1_loop_w1:
	ds_read_b128 v[92:95], v84 offset:0
	ds_read_b128 v[96:99], v84 offset:4096
	ds_read_b128 v[188:191], v85 offset:0
	ds_read_b128 v[192:195], v85 offset:4096
	ds_read_b128 v[100:103], v86 offset:0
	ds_read_b128 v[144:147], v86 offset:4096
	ds_read_b128 v[212:215], v87 offset:0
	ds_read_b128 v[216:219], v87 offset:4096
	ds_read_b128 v[148:151], v88 offset:0
	ds_read_b128 v[152:155], v88 offset:4096
	ds_read_b128 v[220:223], v89 offset:0
	ds_read_b128 v[224:227], v89 offset:4096
	ds_read_b128 v[180:183], v90 offset:0
	ds_read_b128 v[184:187], v90 offset:4096
	ds_read_b128 v[228:231], v91 offset:0
	ds_read_b128 v[252:255], v91 offset:4096
	s_waitcnt lgkmcnt(0)
	s_barrier
	v_mfma_f32_32x32x16_bf16 v[18:33], v[92:95], v[188:191], v[18:33]
	s_mov_b32 m0, s1
	v_mfma_f32_32x32x16_bf16 v[50:65], v[92:95], v[192:195], v[50:65]
	global_load_lds_dwordx4 v[66:67], off
	v_mfma_f32_32x32x16_bf16 v[2:17], v[96:99], v[188:191], v[2:17]
	s_add_i32 m0, s1, 0x400
	v_mfma_f32_32x32x16_bf16 v[34:49], v[96:99], v[192:195], v[34:49]
	global_load_lds_dwordx4 v[70:71], off
	v_mfma_f32_32x32x16_bf16 v[18:33], v[100:103], v[212:215], v[18:33]
	v_mfma_f32_32x32x16_bf16 v[50:65], v[100:103], v[216:219], v[50:65]
	s_add_i32 m0, s1, 0x800
	v_mfma_f32_32x32x16_bf16 v[2:17], v[144:147], v[212:215], v[2:17]
	global_load_lds_dwordx4 v[74:75], off
	v_mfma_f32_32x32x16_bf16 v[34:49], v[144:147], v[216:219], v[34:49]
	v_mfma_f32_32x32x16_bf16 v[18:33], v[148:151], v[220:223], v[18:33]
	s_add_i32 m0, s1, 0xc00
	v_mfma_f32_32x32x16_bf16 v[50:65], v[148:151], v[224:227], v[50:65]
	global_load_lds_dwordx4 v[78:79], off
	v_mfma_f32_32x32x16_bf16 v[2:17], v[152:155], v[220:223], v[2:17]
	s_mov_b32 m0, s8
	v_mfma_f32_32x32x16_bf16 v[34:49], v[152:155], v[224:227], v[34:49]
	global_load_lds_dwordx4 v[68:69], off
	v_lshl_add_u64 v[68:69], v[68:69], 0, s[34:35]
	v_mfma_f32_32x32x16_bf16 v[18:33], v[180:183], v[228:231], v[18:33]
	v_mfma_f32_32x32x16_bf16 v[50:65], v[180:183], v[252:255], v[50:65]
	s_mov_b32 m0, s9
	v_mfma_f32_32x32x16_bf16 v[2:17], v[184:187], v[228:231], v[2:17]
	global_load_lds_dwordx4 v[72:73], off
	v_lshl_add_u64 v[72:73], v[72:73], 0, s[34:35]
	v_mfma_f32_32x32x16_bf16 v[34:49], v[184:187], v[252:255], v[34:49]
	s_waitcnt vmcnt(8)
	s_barrier
	ds_read_b128 v[92:95], v84 offset:32768
	ds_read_b128 v[96:99], v84 offset:36864
	ds_read_b128 v[100:103], v86 offset:32768
	ds_read_b128 v[144:147], v86 offset:36864
	ds_read_b128 v[148:151], v88 offset:32768
	ds_read_b128 v[152:155], v88 offset:36864
	ds_read_b128 v[180:183], v90 offset:32768
	ds_read_b128 v[184:187], v90 offset:36864
	s_waitcnt lgkmcnt(0)
	s_barrier
	v_mfma_f32_32x32x16_bf16 v[104:119], v[92:95], v[188:191], v[104:119]
	s_mov_b32 m0, s6
	v_lshl_add_u64 v[82:83], v[66:67], 0, s[26:27]
	v_mfma_f32_32x32x16_bf16 v[128:143], v[92:95], v[192:195], v[128:143]
	global_load_lds_dwordx4 v[82:83], off
	v_lshl_add_u64 v[66:67], v[66:67], 0, s[34:35]
	v_mfma_f32_32x32x16_bf16 v[196:211], v[96:99], v[188:191], v[196:211]
	s_mov_b32 m0, s13
	v_lshl_add_u64 v[82:83], v[70:71], 0, s[26:27]
	v_mfma_f32_32x32x16_bf16 v[236:251], v[96:99], v[192:195], v[236:251]
	global_load_lds_dwordx4 v[82:83], off
	v_lshl_add_u64 v[70:71], v[70:71], 0, s[34:35]
	v_mfma_f32_32x32x16_bf16 v[104:119], v[100:103], v[212:215], v[104:119]
	v_mfma_f32_32x32x16_bf16 v[128:143], v[100:103], v[216:219], v[128:143]
	s_mov_b32 m0, s15
	v_lshl_add_u64 v[82:83], v[74:75], 0, s[26:27]
	v_mfma_f32_32x32x16_bf16 v[196:211], v[144:147], v[212:215], v[196:211]
	global_load_lds_dwordx4 v[82:83], off
	v_lshl_add_u64 v[74:75], v[74:75], 0, s[34:35]
	v_mfma_f32_32x32x16_bf16 v[236:251], v[144:147], v[216:219], v[236:251]
	v_mfma_f32_32x32x16_bf16 v[104:119], v[148:151], v[220:223], v[104:119]
	s_mov_b32 m0, s17
	v_lshl_add_u64 v[82:83], v[78:79], 0, s[26:27]
	v_mfma_f32_32x32x16_bf16 v[128:143], v[148:151], v[224:227], v[128:143]
	global_load_lds_dwordx4 v[82:83], off
	v_lshl_add_u64 v[78:79], v[78:79], 0, s[34:35]
	v_mfma_f32_32x32x16_bf16 v[196:211], v[152:155], v[220:223], v[196:211]
	s_mov_b32 m0, s10
	v_mfma_f32_32x32x16_bf16 v[236:251], v[152:155], v[224:227], v[236:251]
	global_load_lds_dwordx4 v[76:77], off
	v_lshl_add_u64 v[76:77], v[76:77], 0, s[34:35]
	v_mfma_f32_32x32x16_bf16 v[104:119], v[180:183], v[228:231], v[104:119]
	v_mfma_f32_32x32x16_bf16 v[128:143], v[180:183], v[252:255], v[128:143]
	s_mov_b32 m0, s11
	v_mfma_f32_32x32x16_bf16 v[196:211], v[184:187], v[228:231], v[196:211]
	global_load_lds_dwordx4 v[80:81], off
	v_lshl_add_u64 v[80:81], v[80:81], 0, s[34:35]
	v_mfma_f32_32x32x16_bf16 v[236:251], v[184:187], v[252:255], v[236:251]
	s_waitcnt vmcnt(8)
	s_barrier
	ds_read_b128 v[92:95], v84 offset:0
	ds_read_b128 v[96:99], v84 offset:4096
	ds_read_b128 v[188:191], v85 offset:32768
	ds_read_b128 v[192:195], v85 offset:36864
	ds_read_b128 v[100:103], v86 offset:0
	ds_read_b128 v[144:147], v86 offset:4096
	ds_read_b128 v[212:215], v87 offset:32768
	ds_read_b128 v[216:219], v87 offset:36864
	ds_read_b128 v[148:151], v88 offset:0
	ds_read_b128 v[152:155], v88 offset:4096
	ds_read_b128 v[220:223], v89 offset:32768
	ds_read_b128 v[224:227], v89 offset:36864
	ds_read_b128 v[180:183], v90 offset:0
	ds_read_b128 v[184:187], v90 offset:4096
	ds_read_b128 v[228:231], v91 offset:32768
	ds_read_b128 v[252:255], v91 offset:36864
	s_waitcnt lgkmcnt(0)
	s_barrier
	v_mfma_f32_32x32x16_bf16 v[18:33], v[92:95], v[188:191], v[18:33]
	s_mov_b32 m0, s1
	v_mfma_f32_32x32x16_bf16 v[50:65], v[92:95], v[192:195], v[50:65]
	global_load_lds_dwordx4 v[66:67], off
	v_mfma_f32_32x32x16_bf16 v[2:17], v[96:99], v[188:191], v[2:17]
	s_add_i32 m0, s1, 0x400
	v_mfma_f32_32x32x16_bf16 v[34:49], v[96:99], v[192:195], v[34:49]
	global_load_lds_dwordx4 v[70:71], off
	v_mfma_f32_32x32x16_bf16 v[18:33], v[100:103], v[212:215], v[18:33]
	v_mfma_f32_32x32x16_bf16 v[50:65], v[100:103], v[216:219], v[50:65]
	s_add_i32 m0, s1, 0x800
	v_mfma_f32_32x32x16_bf16 v[2:17], v[144:147], v[212:215], v[2:17]
	global_load_lds_dwordx4 v[74:75], off
	v_mfma_f32_32x32x16_bf16 v[34:49], v[144:147], v[216:219], v[34:49]
	v_mfma_f32_32x32x16_bf16 v[18:33], v[148:151], v[220:223], v[18:33]
	s_add_i32 m0, s1, 0xc00
	v_mfma_f32_32x32x16_bf16 v[50:65], v[148:151], v[224:227], v[50:65]
	global_load_lds_dwordx4 v[78:79], off
	v_mfma_f32_32x32x16_bf16 v[2:17], v[152:155], v[220:223], v[2:17]
	s_mov_b32 m0, s7
	v_mfma_f32_32x32x16_bf16 v[34:49], v[152:155], v[224:227], v[34:49]
	global_load_lds_dwordx4 v[68:69], off
	v_lshl_add_u64 v[68:69], v[68:69], 0, s[34:35]
	v_mfma_f32_32x32x16_bf16 v[18:33], v[180:183], v[228:231], v[18:33]
	v_mfma_f32_32x32x16_bf16 v[50:65], v[180:183], v[252:255], v[50:65]
	s_mov_b32 m0, s14
	v_mfma_f32_32x32x16_bf16 v[2:17], v[184:187], v[228:231], v[2:17]
	global_load_lds_dwordx4 v[72:73], off
	v_lshl_add_u64 v[72:73], v[72:73], 0, s[34:35]
	v_mfma_f32_32x32x16_bf16 v[34:49], v[184:187], v[252:255], v[34:49]
	s_waitcnt vmcnt(8)
	s_barrier
	ds_read_b128 v[92:95], v84 offset:32768
	ds_read_b128 v[96:99], v84 offset:36864
	ds_read_b128 v[100:103], v86 offset:32768
	ds_read_b128 v[144:147], v86 offset:36864
	ds_read_b128 v[148:151], v88 offset:32768
	ds_read_b128 v[152:155], v88 offset:36864
	ds_read_b128 v[180:183], v90 offset:32768
	ds_read_b128 v[184:187], v90 offset:36864
	s_waitcnt lgkmcnt(0)
	s_barrier
	v_mfma_f32_32x32x16_bf16 v[104:119], v[92:95], v[188:191], v[104:119]
	s_mov_b32 m0, s6
	v_lshl_add_u64 v[82:83], v[66:67], 0, s[26:27]
	v_mfma_f32_32x32x16_bf16 v[128:143], v[92:95], v[192:195], v[128:143]
	global_load_lds_dwordx4 v[82:83], off
	v_lshl_add_u64 v[66:67], v[66:67], 0, s[34:35]
	v_mfma_f32_32x32x16_bf16 v[196:211], v[96:99], v[188:191], v[196:211]
	s_mov_b32 m0, s13
	v_lshl_add_u64 v[82:83], v[70:71], 0, s[26:27]
	v_mfma_f32_32x32x16_bf16 v[236:251], v[96:99], v[192:195], v[236:251]
	global_load_lds_dwordx4 v[82:83], off
	v_lshl_add_u64 v[70:71], v[70:71], 0, s[34:35]
	v_mfma_f32_32x32x16_bf16 v[104:119], v[100:103], v[212:215], v[104:119]
	v_mfma_f32_32x32x16_bf16 v[128:143], v[100:103], v[216:219], v[128:143]
	s_mov_b32 m0, s15
	v_lshl_add_u64 v[82:83], v[74:75], 0, s[26:27]
	v_mfma_f32_32x32x16_bf16 v[196:211], v[144:147], v[212:215], v[196:211]
	global_load_lds_dwordx4 v[82:83], off
	v_lshl_add_u64 v[74:75], v[74:75], 0, s[34:35]
	v_mfma_f32_32x32x16_bf16 v[236:251], v[144:147], v[216:219], v[236:251]
	v_mfma_f32_32x32x16_bf16 v[104:119], v[148:151], v[220:223], v[104:119]
	s_mov_b32 m0, s17
	v_lshl_add_u64 v[82:83], v[78:79], 0, s[26:27]
	v_mfma_f32_32x32x16_bf16 v[128:143], v[148:151], v[224:227], v[128:143]
	global_load_lds_dwordx4 v[82:83], off
	v_lshl_add_u64 v[78:79], v[78:79], 0, s[34:35]
	v_mfma_f32_32x32x16_bf16 v[196:211], v[152:155], v[220:223], v[196:211]
	s_mov_b32 m0, s16
	v_mfma_f32_32x32x16_bf16 v[236:251], v[152:155], v[224:227], v[236:251]
	global_load_lds_dwordx4 v[76:77], off
	v_lshl_add_u64 v[76:77], v[76:77], 0, s[34:35]
	v_mfma_f32_32x32x16_bf16 v[104:119], v[180:183], v[228:231], v[104:119]
	v_mfma_f32_32x32x16_bf16 v[128:143], v[180:183], v[252:255], v[128:143]
	s_mov_b32 m0, s25
	v_mfma_f32_32x32x16_bf16 v[196:211], v[184:187], v[228:231], v[196:211]
	global_load_lds_dwordx4 v[80:81], off
	v_lshl_add_u64 v[80:81], v[80:81], 0, s[34:35]
	v_mfma_f32_32x32x16_bf16 v[236:251], v[184:187], v[252:255], v[236:251]
	s_waitcnt vmcnt(8)
	s_barrier
	s_add_i32 s12, s12, 2
	s_cmp_lt_u32 s12, 14
	s_cbranch_scc1 .Lg1_loop_w1
	ds_read_b128 v[92:95], v84 offset:0
	ds_read_b128 v[96:99], v84 offset:4096
	ds_read_b128 v[188:191], v85 offset:0
	ds_read_b128 v[192:195], v85 offset:4096
	ds_read_b128 v[100:103], v86 offset:0
	ds_read_b128 v[144:147], v86 offset:4096
	ds_read_b128 v[212:215], v87 offset:0
	ds_read_b128 v[216:219], v87 offset:4096
	ds_read_b128 v[148:151], v88 offset:0
	ds_read_b128 v[152:155], v88 offset:4096
	ds_read_b128 v[220:223], v89 offset:0
	ds_read_b128 v[224:227], v89 offset:4096
	ds_read_b128 v[180:183], v90 offset:0
	ds_read_b128 v[184:187], v90 offset:4096
	ds_read_b128 v[228:231], v91 offset:0
	ds_read_b128 v[252:255], v91 offset:4096
	s_waitcnt lgkmcnt(0)
	s_barrier
	v_mfma_f32_32x32x16_bf16 v[18:33], v[92:95], v[188:191], v[18:33]
	s_mov_b32 m0, s1
	v_mfma_f32_32x32x16_bf16 v[50:65], v[92:95], v[192:195], v[50:65]
	global_load_lds_dwordx4 v[66:67], off
	v_mfma_f32_32x32x16_bf16 v[2:17], v[96:99], v[188:191], v[2:17]
	s_add_i32 m0, s1, 0x400
	v_mfma_f32_32x32x16_bf16 v[34:49], v[96:99], v[192:195], v[34:49]
	global_load_lds_dwordx4 v[70:71], off
	v_mfma_f32_32x32x16_bf16 v[18:33], v[100:103], v[212:215], v[18:33]
	v_mfma_f32_32x32x16_bf16 v[50:65], v[100:103], v[216:219], v[50:65]
	v_mfma_f32_32x32x16_bf16 v[2:17], v[144:147], v[212:215], v[2:17]
	v_mfma_f32_32x32x16_bf16 v[34:49], v[144:147], v[216:219], v[34:49]
	v_mfma_f32_32x32x16_bf16 v[18:33], v[148:151], v[220:223], v[18:33]
	s_add_i32 m0, s1, 0x800
	v_mfma_f32_32x32x16_bf16 v[50:65], v[148:151], v[224:227], v[50:65]
	global_load_lds_dwordx4 v[74:75], off
	v_mfma_f32_32x32x16_bf16 v[2:17], v[152:155], v[220:223], v[2:17]
	s_add_i32 m0, s1, 0xc00
	v_mfma_f32_32x32x16_bf16 v[34:49], v[152:155], v[224:227], v[34:49]
	global_load_lds_dwordx4 v[78:79], off
	v_mfma_f32_32x32x16_bf16 v[18:33], v[180:183], v[228:231], v[18:33]
	v_mfma_f32_32x32x16_bf16 v[50:65], v[180:183], v[252:255], v[50:65]
	v_mfma_f32_32x32x16_bf16 v[2:17], v[184:187], v[228:231], v[2:17]
	v_mfma_f32_32x32x16_bf16 v[34:49], v[184:187], v[252:255], v[34:49]
	s_waitcnt vmcnt(4)
	s_barrier
	ds_read_b128 v[92:95], v84 offset:32768
	ds_read_b128 v[96:99], v84 offset:36864
	ds_read_b128 v[100:103], v86 offset:32768
	ds_read_b128 v[144:147], v86 offset:36864
	ds_read_b128 v[148:151], v88 offset:32768
	ds_read_b128 v[152:155], v88 offset:36864
	ds_read_b128 v[180:183], v90 offset:32768
	ds_read_b128 v[184:187], v90 offset:36864
	s_waitcnt lgkmcnt(0)
	s_barrier
	v_mfma_f32_32x32x16_bf16 v[104:119], v[92:95], v[188:191], v[104:119]
	s_mov_b32 m0, s6
	v_lshl_add_u64 v[82:83], v[66:67], 0, s[26:27]
	v_mfma_f32_32x32x16_bf16 v[128:143], v[92:95], v[192:195], v[128:143]
	global_load_lds_dwordx4 v[82:83], off
	v_lshl_add_u64 v[66:67], v[66:67], 0, s[34:35]
	v_mfma_f32_32x32x16_bf16 v[196:211], v[96:99], v[188:191], v[196:211]
	s_mov_b32 m0, s13
	v_lshl_add_u64 v[82:83], v[70:71], 0, s[26:27]
	v_mfma_f32_32x32x16_bf16 v[236:251], v[96:99], v[192:195], v[236:251]
	global_load_lds_dwordx4 v[82:83], off
	v_lshl_add_u64 v[70:71], v[70:71], 0, s[34:35]
	v_mfma_f32_32x32x16_bf16 v[104:119], v[100:103], v[212:215], v[104:119]
	v_mfma_f32_32x32x16_bf16 v[128:143], v[100:103], v[216:219], v[128:143]
	v_mfma_f32_32x32x16_bf16 v[196:211], v[144:147], v[212:215], v[196:211]
	v_mfma_f32_32x32x16_bf16 v[236:251], v[144:147], v[216:219], v[236:251]
	v_mfma_f32_32x32x16_bf16 v[104:119], v[148:151], v[220:223], v[104:119]
	s_mov_b32 m0, s15
	v_lshl_add_u64 v[82:83], v[74:75], 0, s[26:27]
	v_mfma_f32_32x32x16_bf16 v[128:143], v[148:151], v[224:227], v[128:143]
	global_load_lds_dwordx4 v[82:83], off
	v_lshl_add_u64 v[74:75], v[74:75], 0, s[34:35]
	v_mfma_f32_32x32x16_bf16 v[196:211], v[152:155], v[220:223], v[196:211]
	s_mov_b32 m0, s17
	v_lshl_add_u64 v[82:83], v[78:79], 0, s[26:27]
	v_mfma_f32_32x32x16_bf16 v[236:251], v[152:155], v[224:227], v[236:251]
	global_load_lds_dwordx4 v[82:83], off
	v_lshl_add_u64 v[78:79], v[78:79], 0, s[34:35]
	v_mfma_f32_32x32x16_bf16 v[104:119], v[180:183], v[228:231], v[104:119]
	v_mfma_f32_32x32x16_bf16 v[128:143], v[180:183], v[252:255], v[128:143]
	v_mfma_f32_32x32x16_bf16 v[196:211], v[184:187], v[228:231], v[196:211]
	v_mfma_f32_32x32x16_bf16 v[236:251], v[184:187], v[252:255], v[236:251]
	s_waitcnt vmcnt(4)
	s_barrier
	ds_read_b128 v[92:95], v84 offset:0
	ds_read_b128 v[96:99], v84 offset:4096
	ds_read_b128 v[188:191], v85 offset:32768
	ds_read_b128 v[192:195], v85 offset:36864
	ds_read_b128 v[100:103], v86 offset:0
	ds_read_b128 v[144:147], v86 offset:4096
	ds_read_b128 v[212:215], v87 offset:32768
	ds_read_b128 v[216:219], v87 offset:36864
	ds_read_b128 v[148:151], v88 offset:0
	ds_read_b128 v[152:155], v88 offset:4096
	ds_read_b128 v[220:223], v89 offset:32768
	ds_read_b128 v[224:227], v89 offset:36864
	ds_read_b128 v[180:183], v90 offset:0
	ds_read_b128 v[184:187], v90 offset:4096
	ds_read_b128 v[228:231], v91 offset:32768
	ds_read_b128 v[252:255], v91 offset:36864
	s_waitcnt lgkmcnt(0)
	s_barrier
	v_mfma_f32_32x32x16_bf16 v[18:33], v[92:95], v[188:191], v[18:33]
	v_mfma_f32_32x32x16_bf16 v[50:65], v[92:95], v[192:195], v[50:65]
	v_mfma_f32_32x32x16_bf16 v[2:17], v[96:99], v[188:191], v[2:17]
	v_mfma_f32_32x32x16_bf16 v[34:49], v[96:99], v[192:195], v[34:49]
	v_mfma_f32_32x32x16_bf16 v[18:33], v[100:103], v[212:215], v[18:33]
	v_mfma_f32_32x32x16_bf16 v[50:65], v[100:103], v[216:219], v[50:65]
	v_mfma_f32_32x32x16_bf16 v[2:17], v[144:147], v[212:215], v[2:17]
	v_mfma_f32_32x32x16_bf16 v[34:49], v[144:147], v[216:219], v[34:49]
	v_mfma_f32_32x32x16_bf16 v[18:33], v[148:151], v[220:223], v[18:33]
	v_mfma_f32_32x32x16_bf16 v[50:65], v[148:151], v[224:227], v[50:65]
	v_mfma_f32_32x32x16_bf16 v[2:17], v[152:155], v[220:223], v[2:17]
	v_mfma_f32_32x32x16_bf16 v[34:49], v[152:155], v[224:227], v[34:49]
	v_mfma_f32_32x32x16_bf16 v[18:33], v[180:183], v[228:231], v[18:33]
	v_mfma_f32_32x32x16_bf16 v[50:65], v[180:183], v[252:255], v[50:65]
	v_mfma_f32_32x32x16_bf16 v[2:17], v[184:187], v[228:231], v[2:17]
	v_mfma_f32_32x32x16_bf16 v[34:49], v[184:187], v[252:255], v[34:49]
	s_waitcnt vmcnt(0)
	s_barrier
	ds_read_b128 v[92:95], v84 offset:32768
	ds_read_b128 v[96:99], v84 offset:36864
	ds_read_b128 v[100:103], v86 offset:32768
	ds_read_b128 v[144:147], v86 offset:36864
	ds_read_b128 v[148:151], v88 offset:32768
	ds_read_b128 v[152:155], v88 offset:36864
	ds_read_b128 v[180:183], v90 offset:32768
	ds_read_b128 v[184:187], v90 offset:36864
	s_waitcnt lgkmcnt(0)
	s_barrier
	v_mfma_f32_32x32x16_bf16 v[104:119], v[92:95], v[188:191], v[104:119]
	v_mfma_f32_32x32x16_bf16 v[128:143], v[92:95], v[192:195], v[128:143]
	v_mfma_f32_32x32x16_bf16 v[196:211], v[96:99], v[188:191], v[196:211]
	v_mfma_f32_32x32x16_bf16 v[236:251], v[96:99], v[192:195], v[236:251]
	v_mfma_f32_32x32x16_bf16 v[104:119], v[100:103], v[212:215], v[104:119]
	v_mfma_f32_32x32x16_bf16 v[128:143], v[100:103], v[216:219], v[128:143]
	v_mfma_f32_32x32x16_bf16 v[196:211], v[144:147], v[212:215], v[196:211]
	v_mfma_f32_32x32x16_bf16 v[236:251], v[144:147], v[216:219], v[236:251]
	v_mfma_f32_32x32x16_bf16 v[104:119], v[148:151], v[220:223], v[104:119]
	v_mfma_f32_32x32x16_bf16 v[128:143], v[148:151], v[224:227], v[128:143]
	v_mfma_f32_32x32x16_bf16 v[196:211], v[152:155], v[220:223], v[196:211]
	v_mfma_f32_32x32x16_bf16 v[236:251], v[152:155], v[224:227], v[236:251]
	v_mfma_f32_32x32x16_bf16 v[104:119], v[180:183], v[228:231], v[104:119]
	v_mfma_f32_32x32x16_bf16 v[128:143], v[180:183], v[252:255], v[128:143]
	v_mfma_f32_32x32x16_bf16 v[196:211], v[184:187], v[228:231], v[196:211]
	v_mfma_f32_32x32x16_bf16 v[236:251], v[184:187], v[252:255], v[236:251]
	s_waitcnt vmcnt(0) lgkmcnt(0)
	s_barrier
	s_branch .LBB0_187
.Lg1_loop_w2:
	ds_read_b128 v[92:95], v84 offset:0
	ds_read_b128 v[96:99], v84 offset:4096
	ds_read_b128 v[188:191], v85 offset:0
	ds_read_b128 v[192:195], v85 offset:4096
	ds_read_b128 v[100:103], v86 offset:0
	ds_read_b128 v[144:147], v86 offset:4096
	ds_read_b128 v[212:215], v87 offset:0
	ds_read_b128 v[216:219], v87 offset:4096
	ds_read_b128 v[148:151], v88 offset:0
	ds_read_b128 v[152:155], v88 offset:4096
	ds_read_b128 v[220:223], v89 offset:0
	ds_read_b128 v[224:227], v89 offset:4096
	ds_read_b128 v[180:183], v90 offset:0
	ds_read_b128 v[184:187], v90 offset:4096
	ds_read_b128 v[228:231], v91 offset:0
	ds_read_b128 v[252:255], v91 offset:4096
	s_waitcnt lgkmcnt(0)
	s_barrier
	v_mfma_f32_32x32x16_bf16 v[18:33], v[92:95], v[188:191], v[18:33]
	s_mov_b32 m0, s1
	v_mfma_f32_32x32x16_bf16 v[50:65], v[92:95], v[192:195], v[50:65]
	global_load_lds_dwordx4 v[66:67], off
	v_mfma_f32_32x32x16_bf16 v[2:17], v[96:99], v[188:191], v[2:17]
	v_mfma_f32_32x32x16_bf16 v[34:49], v[96:99], v[192:195], v[34:49]
	s_add_i32 m0, s1, 0x400
	v_mfma_f32_32x32x16_bf16 v[18:33], v[100:103], v[212:215], v[18:33]
	global_load_lds_dwordx4 v[70:71], off
	v_mfma_f32_32x32x16_bf16 v[50:65], v[100:103], v[216:219], v[50:65]
	v_mfma_f32_32x32x16_bf16 v[2:17], v[144:147], v[212:215], v[2:17]
	s_add_i32 m0, s1, 0x800
	v_mfma_f32_32x32x16_bf16 v[34:49], v[144:147], v[216:219], v[34:49]
	global_load_lds_dwordx4 v[74:75], off
	v_mfma_f32_32x32x16_bf16 v[18:33], v[148:151], v[220:223], v[18:33]
	s_add_i32 m0, s1, 0xc00
	v_mfma_f32_32x32x16_bf16 v[50:65], v[148:151], v[224:227], v[50:65]
	global_load_lds_dwordx4 v[78:79], off
	v_mfma_f32_32x32x16_bf16 v[2:17], v[152:155], v[220:223], v[2:17]
	v_mfma_f32_32x32x16_bf16 v[34:49], v[152:155], v[224:227], v[34:49]
	s_mov_b32 m0, s8
	v_mfma_f32_32x32x16_bf16 v[18:33], v[180:183], v[228:231], v[18:33]
	global_load_lds_dwordx4 v[68:69], off
	v_lshl_add_u64 v[68:69], v[68:69], 0, s[34:35]
	v_mfma_f32_32x32x16_bf16 v[50:65], v[180:183], v[252:255], v[50:65]
	v_mfma_f32_32x32x16_bf16 v[2:17], v[184:187], v[228:231], v[2:17]
	s_mov_b32 m0, s9
	v_mfma_f32_32x32x16_bf16 v[34:49], v[184:187], v[252:255], v[34:49]
	global_load_lds_dwordx4 v[72:73], off
	v_lshl_add_u64 v[72:73], v[72:73], 0, s[34:35]
	s_waitcnt vmcnt(8)
	s_barrier
	ds_read_b128 v[92:95], v84 offset:32768
	ds_read_b128 v[96:99], v84 offset:36864
	ds_read_b128 v[100:103], v86 offset:32768
	ds_read_b128 v[144:147], v86 offset:36864
	ds_read_b128 v[148:151], v88 offset:32768
	ds_read_b128 v[152:155], v88 offset:36864
	ds_read_b128 v[180:183], v90 offset:32768
	ds_read_b128 v[184:187], v90 offset:36864
	s_waitcnt lgkmcnt(0)
	s_barrier
	v_mfma_f32_32x32x16_bf16 v[104:119], v[92:95], v[188:191], v[104:119]
	s_mov_b32 m0, s6
	v_lshl_add_u64 v[82:83], v[66:67], 0, s[26:27]
	v_mfma_f32_32x32x16_bf16 v[128:143], v[92:95], v[192:195], v[128:143]
	global_load_lds_dwordx4 v[82:83], off
	v_lshl_add_u64 v[66:67], v[66:67], 0, s[34:35]
	v_mfma_f32_32x32x16_bf16 v[196:211], v[96:99], v[188:191], v[196:211]
	v_mfma_f32_32x32x16_bf16 v[236:251], v[96:99], v[192:195], v[236:251]
	s_mov_b32 m0, s13
	v_lshl_add_u64 v[82:83], v[70:71], 0, s[26:27]
	v_mfma_f32_32x32x16_bf16 v[104:119], v[100:103], v[212:215], v[104:119]
	global_load_lds_dwordx4 v[82:83], off
	v_lshl_add_u64 v[70:71], v[70:71], 0, s[34:35]
	v_mfma_f32_32x32x16_bf16 v[128:143], v[100:103], v[216:219], v[128:143]
	v_mfma_f32_32x32x16_bf16 v[196:211], v[144:147], v[212:215], v[196:211]
	s_mov_b32 m0, s15
	v_lshl_add_u64 v[82:83], v[74:75], 0, s[26:27]
	v_mfma_f32_32x32x16_bf16 v[236:251], v[144:147], v[216:219], v[236:251]
	global_load_lds_dwordx4 v[82:83], off
	v_lshl_add_u64 v[74:75], v[74:75], 0, s[34:35]
	v_mfma_f32_32x32x16_bf16 v[104:119], v[148:151], v[220:223], v[104:119]
	s_mov_b32 m0, s17
	v_lshl_add_u64 v[82:83], v[78:79], 0, s[26:27]
	v_mfma_f32_32x32x16_bf16 v[128:143], v[148:151], v[224:227], v[128:143]
	global_load_lds_dwordx4 v[82:83], off
	v_lshl_add_u64 v[78:79], v[78:79], 0, s[34:35]
	v_mfma_f32_32x32x16_bf16 v[196:211], v[152:155], v[220:223], v[196:211]
	v_mfma_f32_32x32x16_bf16 v[236:251], v[152:155], v[224:227], v[236:251]
	s_mov_b32 m0, s10
	v_mfma_f32_32x32x16_bf16 v[104:119], v[180:183], v[228:231], v[104:119]
	global_load_lds_dwordx4 v[76:77], off
	v_lshl_add_u64 v[76:77], v[76:77], 0, s[34:35]
	v_mfma_f32_32x32x16_bf16 v[128:143], v[180:183], v[252:255], v[128:143]
	v_mfma_f32_32x32x16_bf16 v[196:211], v[184:187], v[228:231], v[196:211]
	s_mov_b32 m0, s11
	v_mfma_f32_32x32x16_bf16 v[236:251], v[184:187], v[252:255], v[236:251]
	global_load_lds_dwordx4 v[80:81], off
	v_lshl_add_u64 v[80:81], v[80:81], 0, s[34:35]
	s_waitcnt vmcnt(8)
	s_barrier
	ds_read_b128 v[92:95], v84 offset:0
	ds_read_b128 v[96:99], v84 offset:4096
	ds_read_b128 v[188:191], v85 offset:32768
	ds_read_b128 v[192:195], v85 offset:36864
	ds_read_b128 v[100:103], v86 offset:0
	ds_read_b128 v[144:147], v86 offset:4096
	ds_read_b128 v[212:215], v87 offset:32768
	ds_read_b128 v[216:219], v87 offset:36864
	ds_read_b128 v[148:151], v88 offset:0
	ds_read_b128 v[152:155], v88 offset:4096
	ds_read_b128 v[220:223], v89 offset:32768
	ds_read_b128 v[224:227], v89 offset:36864
	ds_read_b128 v[180:183], v90 offset:0
	ds_read_b128 v[184:187], v90 offset:4096
	ds_read_b128 v[228:231], v91 offset:32768
	ds_read_b128 v[252:255], v91 offset:36864
	s_waitcnt lgkmcnt(0)
	s_barrier
	v_mfma_f32_32x32x16_bf16 v[18:33], v[92:95], v[188:191], v[18:33]
	s_mov_b32 m0, s1
	v_mfma_f32_32x32x16_bf16 v[50:65], v[92:95], v[192:195], v[50:65]
	global_load_lds_dwordx4 v[66:67], off
	v_mfma_f32_32x32x16_bf16 v[2:17], v[96:99], v[188:191], v[2:17]
	v_mfma_f32_32x32x16_bf16 v[34:49], v[96:99], v[192:195], v[34:49]
	s_add_i32 m0, s1, 0x400
	v_mfma_f32_32x32x16_bf16 v[18:33], v[100:103], v[212:215], v[18:33]
	global_load_lds_dwordx4 v[70:71], off
	v_mfma_f32_32x32x16_bf16 v[50:65], v[100:103], v[216:219], v[50:65]
	v_mfma_f32_32x32x16_bf16 v[2:17], v[144:147], v[212:215], v[2:17]
	s_add_i32 m0, s1, 0x800
	v_mfma_f32_32x32x16_bf16 v[34:49], v[144:147], v[216:219], v[34:49]
	global_load_lds_dwordx4 v[74:75], off
	v_mfma_f32_32x32x16_bf16 v[18:33], v[148:151], v[220:223], v[18:33]
	s_add_i32 m0, s1, 0xc00
	v_mfma_f32_32x32x16_bf16 v[50:65], v[148:151], v[224:227], v[50:65]
	global_load_lds_dwordx4 v[78:79], off
	v_mfma_f32_32x32x16_bf16 v[2:17], v[152:155], v[220:223], v[2:17]
	v_mfma_f32_32x32x16_bf16 v[34:49], v[152:155], v[224:227], v[34:49]
	s_mov_b32 m0, s7
	v_mfma_f32_32x32x16_bf16 v[18:33], v[180:183], v[228:231], v[18:33]
	global_load_lds_dwordx4 v[68:69], off
	v_lshl_add_u64 v[68:69], v[68:69], 0, s[34:35]
	v_mfma_f32_32x32x16_bf16 v[50:65], v[180:183], v[252:255], v[50:65]
	v_mfma_f32_32x32x16_bf16 v[2:17], v[184:187], v[228:231], v[2:17]
	s_mov_b32 m0, s14
	v_mfma_f32_32x32x16_bf16 v[34:49], v[184:187], v[252:255], v[34:49]
	global_load_lds_dwordx4 v[72:73], off
	v_lshl_add_u64 v[72:73], v[72:73], 0, s[34:35]
	s_waitcnt vmcnt(8)
	s_barrier
	ds_read_b128 v[92:95], v84 offset:32768
	ds_read_b128 v[96:99], v84 offset:36864
	ds_read_b128 v[100:103], v86 offset:32768
	ds_read_b128 v[144:147], v86 offset:36864
	ds_read_b128 v[148:151], v88 offset:32768
	ds_read_b128 v[152:155], v88 offset:36864
	ds_read_b128 v[180:183], v90 offset:32768
	ds_read_b128 v[184:187], v90 offset:36864
	s_waitcnt lgkmcnt(0)
	s_barrier
	v_mfma_f32_32x32x16_bf16 v[104:119], v[92:95], v[188:191], v[104:119]
	s_mov_b32 m0, s6
	v_lshl_add_u64 v[82:83], v[66:67], 0, s[26:27]
	v_mfma_f32_32x32x16_bf16 v[128:143], v[92:95], v[192:195], v[128:143]
	global_load_lds_dwordx4 v[82:83], off
	v_lshl_add_u64 v[66:67], v[66:67], 0, s[34:35]
	v_mfma_f32_32x32x16_bf16 v[196:211], v[96:99], v[188:191], v[196:211]
	v_mfma_f32_32x32x16_bf16 v[236:251], v[96:99], v[192:195], v[236:251]
	s_mov_b32 m0, s13
	v_lshl_add_u64 v[82:83], v[70:71], 0, s[26:27]
	v_mfma_f32_32x32x16_bf16 v[104:119], v[100:103], v[212:215], v[104:119]
	global_load_lds_dwordx4 v[82:83], off
	v_lshl_add_u64 v[70:71], v[70:71], 0, s[34:35]
	v_mfma_f32_32x32x16_bf16 v[128:143], v[100:103], v[216:219], v[128:143]
	v_mfma_f32_32x32x16_bf16 v[196:211], v[144:147], v[212:215], v[196:211]
	s_mov_b32 m0, s15
	v_lshl_add_u64 v[82:83], v[74:75], 0, s[26:27]
	v_mfma_f32_32x32x16_bf16 v[236:251], v[144:147], v[216:219], v[236:251]
	global_load_lds_dwordx4 v[82:83], off
	v_lshl_add_u64 v[74:75], v[74:75], 0, s[34:35]
	v_mfma_f32_32x32x16_bf16 v[104:119], v[148:151], v[220:223], v[104:119]
	s_mov_b32 m0, s17
	v_lshl_add_u64 v[82:83], v[78:79], 0, s[26:27]
	v_mfma_f32_32x32x16_bf16 v[128:143], v[148:151], v[224:227], v[128:143]
	global_load_lds_dwordx4 v[82:83], off
	v_lshl_add_u64 v[78:79], v[78:79], 0, s[34:35]
	v_mfma_f32_32x32x16_bf16 v[196:211], v[152:155], v[220:223], v[196:211]
	v_mfma_f32_32x32x16_bf16 v[236:251], v[152:155], v[224:227], v[236:251]
	s_mov_b32 m0, s16
	v_mfma_f32_32x32x16_bf16 v[104:119], v[180:183], v[228:231], v[104:119]
	global_load_lds_dwordx4 v[76:77], off
	v_lshl_add_u64 v[76:77], v[76:77], 0, s[34:35]
	v_mfma_f32_32x32x16_bf16 v[128:143], v[180:183], v[252:255], v[128:143]
	v_mfma_f32_32x32x16_bf16 v[196:211], v[184:187], v[228:231], v[196:211]
	s_mov_b32 m0, s25
	v_mfma_f32_32x32x16_bf16 v[236:251], v[184:187], v[252:255], v[236:251]
	global_load_lds_dwordx4 v[80:81], off
	v_lshl_add_u64 v[80:81], v[80:81], 0, s[34:35]
	s_waitcnt vmcnt(8)
	s_barrier
	s_add_i32 s12, s12, 2
	s_cmp_lt_u32 s12, 14
	s_cbranch_scc1 .Lg1_loop_w2
	ds_read_b128 v[92:95], v84 offset:0
	ds_read_b128 v[96:99], v84 offset:4096
	ds_read_b128 v[188:191], v85 offset:0
	ds_read_b128 v[192:195], v85 offset:4096
	ds_read_b128 v[100:103], v86 offset:0
	ds_read_b128 v[144:147], v86 offset:4096
	ds_read_b128 v[212:215], v87 offset:0
	ds_read_b128 v[216:219], v87 offset:4096
	ds_read_b128 v[148:151], v88 offset:0
	ds_read_b128 v[152:155], v88 offset:4096
	ds_read_b128 v[220:223], v89 offset:0
	ds_read_b128 v[224:227], v89 offset:4096
	ds_read_b128 v[180:183], v90 offset:0
	ds_read_b128 v[184:187], v90 offset:4096
	ds_read_b128 v[228:231], v91 offset:0
	ds_read_b128 v[252:255], v91 offset:4096
	s_waitcnt lgkmcnt(0)
	s_barrier
	v_mfma_f32_32x32x16_bf16 v[18:33], v[92:95], v[188:191], v[18:33]
	s_mov_b32 m0, s1
	v_mfma_f32_32x32x16_bf16 v[50:65], v[92:95], v[192:195], v[50:65]
	global_load_lds_dwordx4 v[66:67], off
	v_mfma_f32_32x32x16_bf16 v[2:17], v[96:99], v[188:191], v[2:17]
	v_mfma_f32_32x32x16_bf16 v[34:49], v[96:99], v[192:195], v[34:49]
	s_add_i32 m0, s1, 0x400
	v_mfma_f32_32x32x16_bf16 v[18:33], v[100:103], v[212:215], v[18:33]
	global_load_lds_dwordx4 v[70:71], off
	v_mfma_f32_32x32x16_bf16 v[50:65], v[100:103], v[216:219], v[50:65]
	v_mfma_f32_32x32x16_bf16 v[2:17], v[144:147], v[212:215], v[2:17]
	v_mfma_f32_32x32x16_bf16 v[34:49], v[144:147], v[216:219], v[34:49]
	v_mfma_f32_32x32x16_bf16 v[18:33], v[148:151], v[220:223], v[18:33]
	s_add_i32 m0, s1, 0x800
	v_mfma_f32_32x32x16_bf16 v[50:65], v[148:151], v[224:227], v[50:65]
	global_load_lds_dwordx4 v[74:75], off
	v_mfma_f32_32x32x16_bf16 v[2:17], v[152:155], v[220:223], v[2:17]
	v_mfma_f32_32x32x16_bf16 v[34:49], v[152:155], v[224:227], v[34:49]
	s_add_i32 m0, s1, 0xc00
	v_mfma_f32_32x32x16_bf16 v[18:33], v[180:183], v[228:231], v[18:33]
	global_load_lds_dwordx4 v[78:79], off
	v_mfma_f32_32x32x16_bf16 v[50:65], v[180:183], v[252:255], v[50:65]
	v_mfma_f32_32x32x16_bf16 v[2:17], v[184:187], v[228:231], v[2:17]
	v_mfma_f32_32x32x16_bf16 v[34:49], v[184:187], v[252:255], v[34:49]
	s_waitcnt vmcnt(4)
	s_barrier
	ds_read_b128 v[92:95], v84 offset:32768
	ds_read_b128 v[96:99], v84 offset:36864
	ds_read_b128 v[100:103], v86 offset:32768
	ds_read_b128 v[144:147], v86 offset:36864
	ds_read_b128 v[148:151], v88 offset:32768
	ds_read_b128 v[152:155], v88 offset:36864
	ds_read_b128 v[180:183], v90 offset:32768
	ds_read_b128 v[184:187], v90 offset:36864
	s_waitcnt lgkmcnt(0)
	s_barrier
	v_mfma_f32_32x32x16_bf16 v[104:119], v[92:95], v[188:191], v[104:119]
	s_mov_b32 m0, s6
	v_lshl_add_u64 v[82:83], v[66:67], 0, s[26:27]
	v_mfma_f32_32x32x16_bf16 v[128:143], v[92:95], v[192:195], v[128:143]
	global_load_lds_dwordx4 v[82:83], off
	v_lshl_add_u64 v[66:67], v[66:67], 0, s[34:35]
	v_mfma_f32_32x32x16_bf16 v[196:211], v[96:99], v[188:191], v[196:211]
	v_mfma_f32_32x32x16_bf16 v[236:251], v[96:99], v[192:195], v[236:251]
	s_mov_b32 m0, s13
	v_lshl_add_u64 v[82:83], v[70:71], 0, s[26:27]
	v_mfma_f32_32x32x16_bf16 v[104:119], v[100:103], v[212:215], v[104:119]
	global_load_lds_dwordx4 v[82:83], off
	v_lshl_add_u64 v[70:71], v[70:71], 0, s[34:35]
	v_mfma_f32_32x32x16_bf16 v[128:143], v[100:103], v[216:219], v[128:143]
	v_mfma_f32_32x32x16_bf16 v[196:211], v[144:147], v[212:215], v[196:211]
	v_mfma_f32_32x32x16_bf16 v[236:251], v[144:147], v[216:219], v[236:251]
	v_mfma_f32_32x32x16_bf16 v[104:119], v[148:151], v[220:223], v[104:119]
	s_mov_b32 m0, s15
	v_lshl_add_u64 v[82:83], v[74:75], 0, s[26:27]
	v_mfma_f32_32x32x16_bf16 v[128:143], v[148:151], v[224:227], v[128:143]
	global_load_lds_dwordx4 v[82:83], off
	v_lshl_add_u64 v[74:75], v[74:75], 0, s[34:35]
	v_mfma_f32_32x32x16_bf16 v[196:211], v[152:155], v[220:223], v[196:211]
	v_mfma_f32_32x32x16_bf16 v[236:251], v[152:155], v[224:227], v[236:251]
	s_mov_b32 m0, s17
	v_lshl_add_u64 v[82:83], v[78:79], 0, s[26:27]
	v_mfma_f32_32x32x16_bf16 v[104:119], v[180:183], v[228:231], v[104:119]
	global_load_lds_dwordx4 v[82:83], off
	v_lshl_add_u64 v[78:79], v[78:79], 0, s[34:35]
	v_mfma_f32_32x32x16_bf16 v[128:143], v[180:183], v[252:255], v[128:143]
	v_mfma_f32_32x32x16_bf16 v[196:211], v[184:187], v[228:231], v[196:211]
	v_mfma_f32_32x32x16_bf16 v[236:251], v[184:187], v[252:255], v[236:251]
	s_waitcnt vmcnt(4)
	s_barrier
	ds_read_b128 v[92:95], v84 offset:0
	ds_read_b128 v[96:99], v84 offset:4096
	ds_read_b128 v[188:191], v85 offset:32768
	ds_read_b128 v[192:195], v85 offset:36864
	ds_read_b128 v[100:103], v86 offset:0
	ds_read_b128 v[144:147], v86 offset:4096
	ds_read_b128 v[212:215], v87 offset:32768
	ds_read_b128 v[216:219], v87 offset:36864
	ds_read_b128 v[148:151], v88 offset:0
	ds_read_b128 v[152:155], v88 offset:4096
	ds_read_b128 v[220:223], v89 offset:32768
	ds_read_b128 v[224:227], v89 offset:36864
	ds_read_b128 v[180:183], v90 offset:0
	ds_read_b128 v[184:187], v90 offset:4096
	ds_read_b128 v[228:231], v91 offset:32768
	ds_read_b128 v[252:255], v91 offset:36864
	s_waitcnt lgkmcnt(0)
	s_barrier
	v_mfma_f32_32x32x16_bf16 v[18:33], v[92:95], v[188:191], v[18:33]
	v_mfma_f32_32x32x16_bf16 v[50:65], v[92:95], v[192:195], v[50:65]
	v_mfma_f32_32x32x16_bf16 v[2:17], v[96:99], v[188:191], v[2:17]
	v_mfma_f32_32x32x16_bf16 v[34:49], v[96:99], v[192:195], v[34:49]
	v_mfma_f32_32x32x16_bf16 v[18:33], v[100:103], v[212:215], v[18:33]
	v_mfma_f32_32x32x16_bf16 v[50:65], v[100:103], v[216:219], v[50:65]
	v_mfma_f32_32x32x16_bf16 v[2:17], v[144:147], v[212:215], v[2:17]
	v_mfma_f32_32x32x16_bf16 v[34:49], v[144:147], v[216:219], v[34:49]
	v_mfma_f32_32x32x16_bf16 v[18:33], v[148:151], v[220:223], v[18:33]
	v_mfma_f32_32x32x16_bf16 v[50:65], v[148:151], v[224:227], v[50:65]
	v_mfma_f32_32x32x16_bf16 v[2:17], v[152:155], v[220:223], v[2:17]
	v_mfma_f32_32x32x16_bf16 v[34:49], v[152:155], v[224:227], v[34:49]
	v_mfma_f32_32x32x16_bf16 v[18:33], v[180:183], v[228:231], v[18:33]
	v_mfma_f32_32x32x16_bf16 v[50:65], v[180:183], v[252:255], v[50:65]
	v_mfma_f32_32x32x16_bf16 v[2:17], v[184:187], v[228:231], v[2:17]
	v_mfma_f32_32x32x16_bf16 v[34:49], v[184:187], v[252:255], v[34:49]
	s_waitcnt vmcnt(0)
	s_barrier
	ds_read_b128 v[92:95], v84 offset:32768
	ds_read_b128 v[96:99], v84 offset:36864
	ds_read_b128 v[100:103], v86 offset:32768
	ds_read_b128 v[144:147], v86 offset:36864
	ds_read_b128 v[148:151], v88 offset:32768
	ds_read_b128 v[152:155], v88 offset:36864
	ds_read_b128 v[180:183], v90 offset:32768
	ds_read_b128 v[184:187], v90 offset:36864
	s_waitcnt lgkmcnt(0)
	s_barrier
	v_mfma_f32_32x32x16_bf16 v[104:119], v[92:95], v[188:191], v[104:119]
	v_mfma_f32_32x32x16_bf16 v[128:143], v[92:95], v[192:195], v[128:143]
	v_mfma_f32_32x32x16_bf16 v[196:211], v[96:99], v[188:191], v[196:211]
	v_mfma_f32_32x32x16_bf16 v[236:251], v[96:99], v[192:195], v[236:251]
	v_mfma_f32_32x32x16_bf16 v[104:119], v[100:103], v[212:215], v[104:119]
	v_mfma_f32_32x32x16_bf16 v[128:143], v[100:103], v[216:219], v[128:143]
	v_mfma_f32_32x32x16_bf16 v[196:211], v[144:147], v[212:215], v[196:211]
	v_mfma_f32_32x32x16_bf16 v[236:251], v[144:147], v[216:219], v[236:251]
	v_mfma_f32_32x32x16_bf16 v[104:119], v[148:151], v[220:223], v[104:119]
	v_mfma_f32_32x32x16_bf16 v[128:143], v[148:151], v[224:227], v[128:143]
	v_mfma_f32_32x32x16_bf16 v[196:211], v[152:155], v[220:223], v[196:211]
	v_mfma_f32_32x32x16_bf16 v[236:251], v[152:155], v[224:227], v[236:251]
	v_mfma_f32_32x32x16_bf16 v[104:119], v[180:183], v[228:231], v[104:119]
	v_mfma_f32_32x32x16_bf16 v[128:143], v[180:183], v[252:255], v[128:143]
	v_mfma_f32_32x32x16_bf16 v[196:211], v[184:187], v[228:231], v[196:211]
	v_mfma_f32_32x32x16_bf16 v[236:251], v[184:187], v[252:255], v[236:251]
	s_waitcnt vmcnt(0) lgkmcnt(0)
	s_barrier
	s_branch .LBB0_187
.Lg1_loop_w3:
	ds_read_b128 v[92:95], v84 offset:0
	ds_read_b128 v[96:99], v84 offset:4096
	ds_read_b128 v[188:191], v85 offset:0
	ds_read_b128 v[192:195], v85 offset:4096
	ds_read_b128 v[100:103], v86 offset:0
	ds_read_b128 v[144:147], v86 offset:4096
	ds_read_b128 v[212:215], v87 offset:0
	ds_read_b128 v[216:219], v87 offset:4096
	ds_read_b128 v[148:151], v88 offset:0
	ds_read_b128 v[152:155], v88 offset:4096
	ds_read_b128 v[220:223], v89 offset:0
	ds_read_b128 v[224:227], v89 offset:4096
	ds_read_b128 v[180:183], v90 offset:0
	ds_read_b128 v[184:187], v90 offset:4096
	ds_read_b128 v[228:231], v91 offset:0
	ds_read_b128 v[252:255], v91 offset:4096
	s_waitcnt lgkmcnt(0)
	s_barrier
	v_mfma_f32_32x32x16_bf16 v[18:33], v[92:95], v[188:191], v[18:33]
	v_mfma_f32_32x32x16_bf16 v[50:65], v[92:95], v[192:195], v[50:65]
	s_mov_b32 m0, s1
	v_mfma_f32_32x32x16_bf16 v[2:17], v[96:99], v[188:191], v[2:17]
	global_load_lds_dwordx4 v[66:67], off
	v_mfma_f32_32x32x16_bf16 v[34:49], v[96:99], v[192:195], v[34:49]
	v_mfma_f32_32x32x16_bf16 v[18:33], v[100:103], v[212:215], v[18:33]
	s_add_i32 m0, s1, 0x400
	v_mfma_f32_32x32x16_bf16 v[50:65], v[100:103], v[216:219], v[50:65]
	global_load_lds_dwordx4 v[70:71], off
	v_mfma_f32_32x32x16_bf16 v[2:17], v[144:147], v[212:215], v[2:17]
	s_add_i32 m0, s1, 0x800
	v_mfma_f32_32x32x16_bf16 v[34:49], v[144:147], v[216:219], v[34:49]
	global_load_lds_dwordx4 v[74:75], off
	v_mfma_f32_32x32x16_bf16 v[18:33], v[148:151], v[220:223], v[18:33]
	v_mfma_f32_32x32x16_bf16 v[50:65], v[148:151], v[224:227], v[50:65]
	s_add_i32 m0, s1, 0xc00
	v_mfma_f32_32x32x16_bf16 v[2:17], v[152:155], v[220:223], v[2:17]
	global_load_lds_dwordx4 v[78:79], off
	v_mfma_f32_32x32x16_bf16 v[34:49], v[152:155], v[224:227], v[34:49]
	v_mfma_f32_32x32x16_bf16 v[18:33], v[180:183], v[228:231], v[18:33]
	s_mov_b32 m0, s8
	v_mfma_f32_32x32x16_bf16 v[50:65], v[180:183], v[252:255], v[50:65]
	global_load_lds_dwordx4 v[68:69], off
	v_lshl_add_u64 v[68:69], v[68:69], 0, s[34:35]
	v_mfma_f32_32x32x16_bf16 v[2:17], v[184:187], v[228:231], v[2:17]
	s_mov_b32 m0, s9
	v_mfma_f32_32x32x16_bf16 v[34:49], v[184:187], v[252:255], v[34:49]
	global_load_lds_dwordx4 v[72:73], off
	v_lshl_add_u64 v[72:73], v[72:73], 0, s[34:35]
	s_waitcnt vmcnt(8)
	s_barrier
	ds_read_b128 v[92:95], v84 offset:32768
	ds_read_b128 v[96:99], v84 offset:36864
	ds_read_b128 v[100:103], v86 offset:32768
	ds_read_b128 v[144:147], v86 offset:36864
	ds_read_b128 v[148:151], v88 offset:32768
	ds_read_b128 v[152:155], v88 offset:36864
	ds_read_b128 v[180:183], v90 offset:32768
	ds_read_b128 v[184:187], v90 offset:36864
	s_waitcnt lgkmcnt(0)
	s_barrier
	v_mfma_f32_32x32x16_bf16 v[104:119], v[92:95], v[188:191], v[104:119]
	v_mfma_f32_32x32x16_bf16 v[128:143], v[92:95], v[192:195], v[128:143]
	s_mov_b32 m0, s6
	v_lshl_add_u64 v[82:83], v[66:67], 0, s[26:27]
	v_mfma_f32_32x32x16_bf16 v[196:211], v[96:99], v[188:191], v[196:211]
	global_load_lds_dwordx4 v[82:83], off
	v_lshl_add_u64 v[66:67], v[66:67], 0, s[34:35]
	v_mfma_f32_32x32x16_bf16 v[236:251], v[96:99], v[192:195], v[236:251]
	v_mfma_f32_32x32x16_bf16 v[104:119], v[100:103], v[212:215], v[104:119]
	s_mov_b32 m0, s13
	v_lshl_add_u64 v[82:83], v[70:71], 0, s[26:27]
	v_mfma_f32_32x32x16_bf16 v[128:143], v[100:103], v[216:219], v[128:143]
	global_load_lds_dwordx4 v[82:83], off
	v_lshl_add_u64 v[70:71], v[70:71], 0, s[34:35]
	v_mfma_f32_32x32x16_bf16 v[196:211], v[144:147], v[212:215], v[196:211]
	s_mov_b32 m0, s15
	v_lshl_add_u64 v[82:83], v[74:75], 0, s[26:27]
	v_mfma_f32_32x32x16_bf16 v[236:251], v[144:147], v[216:219], v[236:251]
	global_load_lds_dwordx4 v[82:83], off
	v_lshl_add_u64 v[74:75], v[74:75], 0, s[34:35]
	v_mfma_f32_32x32x16_bf16 v[104:119], v[148:151], v[220:223], v[104:119]
	v_mfma_f32_32x32x16_bf16 v[128:143], v[148:151], v[224:227], v[128:143]
	s_mov_b32 m0, s17
	v_lshl_add_u64 v[82:83], v[78:79], 0, s[26:27]
	v_mfma_f32_32x32x16_bf16 v[196:211], v[152:155], v[220:223], v[196:211]
	global_load_lds_dwordx4 v[82:83], off
	v_lshl_add_u64 v[78:79], v[78:79], 0, s[34:35]
	v_mfma_f32_32x32x16_bf16 v[236:251], v[152:155], v[224:227], v[236:251]
	v_mfma_f32_32x32x16_bf16 v[104:119], v[180:183], v[228:231], v[104:119]
	s_mov_b32 m0, s10
	v_mfma_f32_32x32x16_bf16 v[128:143], v[180:183], v[252:255], v[128:143]
	global_load_lds_dwordx4 v[76:77], off
	v_lshl_add_u64 v[76:77], v[76:77], 0, s[34:35]
	v_mfma_f32_32x32x16_bf16 v[196:211], v[184:187], v[228:231], v[196:211]
	s_mov_b32 m0, s11
	v_mfma_f32_32x32x16_bf16 v[236:251], v[184:187], v[252:255], v[236:251]
	global_load_lds_dwordx4 v[80:81], off
	v_lshl_add_u64 v[80:81], v[80:81], 0, s[34:35]
	s_waitcnt vmcnt(8)
	s_barrier
	ds_read_b128 v[92:95], v84 offset:0
	ds_read_b128 v[96:99], v84 offset:4096
	ds_read_b128 v[188:191], v85 offset:32768
	ds_read_b128 v[192:195], v85 offset:36864
	ds_read_b128 v[100:103], v86 offset:0
	ds_read_b128 v[144:147], v86 offset:4096
	ds_read_b128 v[212:215], v87 offset:32768
	ds_read_b128 v[216:219], v87 offset:36864
	ds_read_b128 v[148:151], v88 offset:0
	ds_read_b128 v[152:155], v88 offset:4096
	ds_read_b128 v[220:223], v89 offset:32768
	ds_read_b128 v[224:227], v89 offset:36864
	ds_read_b128 v[180:183], v90 offset:0
	ds_read_b128 v[184:187], v90 offset:4096
	ds_read_b128 v[228:231], v91 offset:32768
	ds_read_b128 v[252:255], v91 offset:36864
	s_waitcnt lgkmcnt(0)
	s_barrier
	v_mfma_f32_32x32x16_bf16 v[18:33], v[92:95], v[188:191], v[18:33]
	v_mfma_f32_32x32x16_bf16 v[50:65], v[92:95], v[192:195], v[50:65]
	s_mov_b32 m0, s1
	v_mfma_f32_32x32x16_bf16 v[2:17], v[96:99], v[188:191], v[2:17]
	global_load_lds_dwordx4 v[66:67], off
	v_mfma_f32_32x32x16_bf16 v[34:49], v[96:99], v[192:195], v[34:49]
	v_mfma_f32_32x32x16_bf16 v[18:33], v[100:103], v[212:215], v[18:33]
	s_add_i32 m0, s1, 0x400
	v_mfma_f32_32x32x16_bf16 v[50:65], v[100:103], v[216:219], v[50:65]
	global_load_lds_dwordx4 v[70:71], off
	v_mfma_f32_32x32x16_bf16 v[2:17], v[144:147], v[212:215], v[2:17]
	s_add_i32 m0, s1, 0x800
	v_mfma_f32_32x32x16_bf16 v[34:49], v[144:147], v[216:219], v[34:49]
	global_load_lds_dwordx4 v[74:75], off
	v_mfma_f32_32x32x16_bf16 v[18:33], v[148:151], v[220:223], v[18:33]
	v_mfma_f32_32x32x16_bf16 v[50:65], v[148:151], v[224:227], v[50:65]
	s_add_i32 m0, s1, 0xc00
	v_mfma_f32_32x32x16_bf16 v[2:17], v[152:155], v[220:223], v[2:17]
	global_load_lds_dwordx4 v[78:79], off
	v_mfma_f32_32x32x16_bf16 v[34:49], v[152:155], v[224:227], v[34:49]
	v_mfma_f32_32x32x16_bf16 v[18:33], v[180:183], v[228:231], v[18:33]
	s_mov_b32 m0, s7
	v_mfma_f32_32x32x16_bf16 v[50:65], v[180:183], v[252:255], v[50:65]
	global_load_lds_dwordx4 v[68:69], off
	v_lshl_add_u64 v[68:69], v[68:69], 0, s[34:35]
	v_mfma_f32_32x32x16_bf16 v[2:17], v[184:187], v[228:231], v[2:17]
	s_mov_b32 m0, s14
	v_mfma_f32_32x32x16_bf16 v[34:49], v[184:187], v[252:255], v[34:49]
	global_load_lds_dwordx4 v[72:73], off
	v_lshl_add_u64 v[72:73], v[72:73], 0, s[34:35]
	s_waitcnt vmcnt(8)
	s_barrier
	ds_read_b128 v[92:95], v84 offset:32768
	ds_read_b128 v[96:99], v84 offset:36864
	ds_read_b128 v[100:103], v86 offset:32768
	ds_read_b128 v[144:147], v86 offset:36864
	ds_read_b128 v[148:151], v88 offset:32768
	ds_read_b128 v[152:155], v88 offset:36864
	ds_read_b128 v[180:183], v90 offset:32768
	ds_read_b128 v[184:187], v90 offset:36864
	s_waitcnt lgkmcnt(0)
	s_barrier
	v_mfma_f32_32x32x16_bf16 v[104:119], v[92:95], v[188:191], v[104:119]
	v_mfma_f32_32x32x16_bf16 v[128:143], v[92:95], v[192:195], v[128:143]
	s_mov_b32 m0, s6
	v_lshl_add_u64 v[82:83], v[66:67], 0, s[26:27]
	v_mfma_f32_32x32x16_bf16 v[196:211], v[96:99], v[188:191], v[196:211]
	global_load_lds_dwordx4 v[82:83], off
	v_lshl_add_u64 v[66:67], v[66:67], 0, s[34:35]
	v_mfma_f32_32x32x16_bf16 v[236:251], v[96:99], v[192:195], v[236:251]
	v_mfma_f32_32x32x16_bf16 v[104:119], v[100:103], v[212:215], v[104:119]
	s_mov_b32 m0, s13
	v_lshl_add_u64 v[82:83], v[70:71], 0, s[26:27]
	v_mfma_f32_32x32x16_bf16 v[128:143], v[100:103], v[216:219], v[128:143]
	global_load_lds_dwordx4 v[82:83], off
	v_lshl_add_u64 v[70:71], v[70:71], 0, s[34:35]
	v_mfma_f32_32x32x16_bf16 v[196:211], v[144:147], v[212:215], v[196:211]
	s_mov_b32 m0, s15
	v_lshl_add_u64 v[82:83], v[74:75], 0, s[26:27]
	v_mfma_f32_32x32x16_bf16 v[236:251], v[144:147], v[216:219], v[236:251]
	global_load_lds_dwordx4 v[82:83], off
	v_lshl_add_u64 v[74:75], v[74:75], 0, s[34:35]
	v_mfma_f32_32x32x16_bf16 v[104:119], v[148:151], v[220:223], v[104:119]
	v_mfma_f32_32x32x16_bf16 v[128:143], v[148:151], v[224:227], v[128:143]
	s_mov_b32 m0, s17
	v_lshl_add_u64 v[82:83], v[78:79], 0, s[26:27]
	v_mfma_f32_32x32x16_bf16 v[196:211], v[152:155], v[220:223], v[196:211]
	global_load_lds_dwordx4 v[82:83], off
	v_lshl_add_u64 v[78:79], v[78:79], 0, s[34:35]
	v_mfma_f32_32x32x16_bf16 v[236:251], v[152:155], v[224:227], v[236:251]
	v_mfma_f32_32x32x16_bf16 v[104:119], v[180:183], v[228:231], v[104:119]
	s_mov_b32 m0, s16
	v_mfma_f32_32x32x16_bf16 v[128:143], v[180:183], v[252:255], v[128:143]
	global_load_lds_dwordx4 v[76:77], off
	v_lshl_add_u64 v[76:77], v[76:77], 0, s[34:35]
	v_mfma_f32_32x32x16_bf16 v[196:211], v[184:187], v[228:231], v[196:211]
	s_mov_b32 m0, s25
	v_mfma_f32_32x32x16_bf16 v[236:251], v[184:187], v[252:255], v[236:251]
	global_load_lds_dwordx4 v[80:81], off
	v_lshl_add_u64 v[80:81], v[80:81], 0, s[34:35]
	s_waitcnt vmcnt(8)
	s_barrier
	s_add_i32 s12, s12, 2
	s_cmp_lt_u32 s12, 14
	s_cbranch_scc1 .Lg1_loop_w3
	ds_read_b128 v[92:95], v84 offset:0
	ds_read_b128 v[96:99], v84 offset:4096
	ds_read_b128 v[188:191], v85 offset:0
	ds_read_b128 v[192:195], v85 offset:4096
	ds_read_b128 v[100:103], v86 offset:0
	ds_read_b128 v[144:147], v86 offset:4096
	ds_read_b128 v[212:215], v87 offset:0
	ds_read_b128 v[216:219], v87 offset:4096
	ds_read_b128 v[148:151], v88 offset:0
	ds_read_b128 v[152:155], v88 offset:4096
	ds_read_b128 v[220:223], v89 offset:0
	ds_read_b128 v[224:227], v89 offset:4096
	ds_read_b128 v[180:183], v90 offset:0
	ds_read_b128 v[184:187], v90 offset:4096
	ds_read_b128 v[228:231], v91 offset:0
	ds_read_b128 v[252:255], v91 offset:4096
	s_waitcnt lgkmcnt(0)
	s_barrier
	v_mfma_f32_32x32x16_bf16 v[18:33], v[92:95], v[188:191], v[18:33]
	v_mfma_f32_32x32x16_bf16 v[50:65], v[92:95], v[192:195], v[50:65]
	s_mov_b32 m0, s1
	v_mfma_f32_32x32x16_bf16 v[2:17], v[96:99], v[188:191], v[2:17]
	global_load_lds_dwordx4 v[66:67], off
	v_mfma_f32_32x32x16_bf16 v[34:49], v[96:99], v[192:195], v[34:49]
	v_mfma_f32_32x32x16_bf16 v[18:33], v[100:103], v[212:215], v[18:33]
	s_add_i32 m0, s1, 0x400
	v_mfma_f32_32x32x16_bf16 v[50:65], v[100:103], v[216:219], v[50:65]
	global_load_lds_dwordx4 v[70:71], off
	v_mfma_f32_32x32x16_bf16 v[2:17], v[144:147], v[212:215], v[2:17]
	v_mfma_f32_32x32x16_bf16 v[34:49], v[144:147], v[216:219], v[34:49]
	v_mfma_f32_32x32x16_bf16 v[18:33], v[148:151], v[220:223], v[18:33]
	v_mfma_f32_32x32x16_bf16 v[50:65], v[148:151], v[224:227], v[50:65]
	s_add_i32 m0, s1, 0x800
	v_mfma_f32_32x32x16_bf16 v[2:17], v[152:155], v[220:223], v[2:17]
	global_load_lds_dwordx4 v[74:75], off
	v_mfma_f32_32x32x16_bf16 v[34:49], v[152:155], v[224:227], v[34:49]
	v_mfma_f32_32x32x16_bf16 v[18:33], v[180:183], v[228:231], v[18:33]
	s_add_i32 m0, s1, 0xc00
	v_mfma_f32_32x32x16_bf16 v[50:65], v[180:183], v[252:255], v[50:65]
	global_load_lds_dwordx4 v[78:79], off
	v_mfma_f32_32x32x16_bf16 v[2:17], v[184:187], v[228:231], v[2:17]
	v_mfma_f32_32x32x16_bf16 v[34:49], v[184:187], v[252:255], v[34:49]
	s_waitcnt vmcnt(4)
	s_barrier
	ds_read_b128 v[92:95], v84 offset:32768
	ds_read_b128 v[96:99], v84 offset:36864
	ds_read_b128 v[100:103], v86 offset:32768
	ds_read_b128 v[144:147], v86 offset:36864
	ds_read_b128 v[148:151], v88 offset:32768
	ds_read_b128 v[152:155], v88 offset:36864
	ds_read_b128 v[180:183], v90 offset:32768
	ds_read_b128 v[184:187], v90 offset:36864
	s_waitcnt lgkmcnt(0)
	s_barrier
	v_mfma_f32_32x32x16_bf16 v[104:119], v[92:95], v[188:191], v[104:119]
	v_mfma_f32_32x32x16_bf16 v[128:143], v[92:95], v[192:195], v[128:143]
	s_mov_b32 m0, s6
	v_lshl_add_u64 v[82:83], v[66:67], 0, s[26:27]
	v_mfma_f32_32x32x16_bf16 v[196:211], v[96:99], v[188:191], v[196:211]
	global_load_lds_dwordx4 v[82:83], off
	v_lshl_add_u64 v[66:67], v[66:67], 0, s[34:35]
	v_mfma_f32_32x32x16_bf16 v[236:251], v[96:99], v[192:195], v[236:251]
	v_mfma_f32_32x32x16_bf16 v[104:119], v[100:103], v[212:215], v[104:119]
	s_mov_b32 m0, s13
	v_lshl_add_u64 v[82:83], v[70:71], 0, s[26:27]
	v_mfma_f32_32x32x16_bf16 v[128:143], v[100:103], v[216:219], v[128:143]
	global_load_lds_dwordx4 v[82:83], off
	v_lshl_add_u64 v[70:71], v[70:71], 0, s[34:35]
	v_mfma_f32_32x32x16_bf16 v[196:211], v[144:147], v[212:215], v[196:211]
	v_mfma_f32_32x32x16_bf16 v[236:251], v[144:147], v[216:219], v[236:251]
	v_mfma_f32_32x32x16_bf16 v[104:119], v[148:151], v[220:223], v[104:119]
	v_mfma_f32_32x32x16_bf16 v[128:143], v[148:151], v[224:227], v[128:143]
	s_mov_b32 m0, s15
	v_lshl_add_u64 v[82:83], v[74:75], 0, s[26:27]
	v_mfma_f32_32x32x16_bf16 v[196:211], v[152:155], v[220:223], v[196:211]
	global_load_lds_dwordx4 v[82:83], off
	v_lshl_add_u64 v[74:75], v[74:75], 0, s[34:35]
	v_mfma_f32_32x32x16_bf16 v[236:251], v[152:155], v[224:227], v[236:251]
	v_mfma_f32_32x32x16_bf16 v[104:119], v[180:183], v[228:231], v[104:119]
	s_mov_b32 m0, s17
	v_lshl_add_u64 v[82:83], v[78:79], 0, s[26:27]
	v_mfma_f32_32x32x16_bf16 v[128:143], v[180:183], v[252:255], v[128:143]
	global_load_lds_dwordx4 v[82:83], off
	v_lshl_add_u64 v[78:79], v[78:79], 0, s[34:35]
	v_mfma_f32_32x32x16_bf16 v[196:211], v[184:187], v[228:231], v[196:211]
	v_mfma_f32_32x32x16_bf16 v[236:251], v[184:187], v[252:255], v[236:251]
	s_waitcnt vmcnt(4)
	s_barrier
	ds_read_b128 v[92:95], v84 offset:0
	ds_read_b128 v[96:99], v84 offset:4096
	ds_read_b128 v[188:191], v85 offset:32768
	ds_read_b128 v[192:195], v85 offset:36864
	ds_read_b128 v[100:103], v86 offset:0
	ds_read_b128 v[144:147], v86 offset:4096
	ds_read_b128 v[212:215], v87 offset:32768
	ds_read_b128 v[216:219], v87 offset:36864
	ds_read_b128 v[148:151], v88 offset:0
	ds_read_b128 v[152:155], v88 offset:4096
	ds_read_b128 v[220:223], v89 offset:32768
	ds_read_b128 v[224:227], v89 offset:36864
	ds_read_b128 v[180:183], v90 offset:0
	ds_read_b128 v[184:187], v90 offset:4096
	ds_read_b128 v[228:231], v91 offset:32768
	ds_read_b128 v[252:255], v91 offset:36864
	s_waitcnt lgkmcnt(0)
	s_barrier
	v_mfma_f32_32x32x16_bf16 v[18:33], v[92:95], v[188:191], v[18:33]
	v_mfma_f32_32x32x16_bf16 v[50:65], v[92:95], v[192:195], v[50:65]
	v_mfma_f32_32x32x16_bf16 v[2:17], v[96:99], v[188:191], v[2:17]
	v_mfma_f32_32x32x16_bf16 v[34:49], v[96:99], v[192:195], v[34:49]
	v_mfma_f32_32x32x16_bf16 v[18:33], v[100:103], v[212:215], v[18:33]
	v_mfma_f32_32x32x16_bf16 v[50:65], v[100:103], v[216:219], v[50:65]
	v_mfma_f32_32x32x16_bf16 v[2:17], v[144:147], v[212:215], v[2:17]
	v_mfma_f32_32x32x16_bf16 v[34:49], v[144:147], v[216:219], v[34:49]
	v_mfma_f32_32x32x16_bf16 v[18:33], v[148:151], v[220:223], v[18:33]
	v_mfma_f32_32x32x16_bf16 v[50:65], v[148:151], v[224:227], v[50:65]
	v_mfma_f32_32x32x16_bf16 v[2:17], v[152:155], v[220:223], v[2:17]
	v_mfma_f32_32x32x16_bf16 v[34:49], v[152:155], v[224:227], v[34:49]
	v_mfma_f32_32x32x16_bf16 v[18:33], v[180:183], v[228:231], v[18:33]
	v_mfma_f32_32x32x16_bf16 v[50:65], v[180:183], v[252:255], v[50:65]
	v_mfma_f32_32x32x16_bf16 v[2:17], v[184:187], v[228:231], v[2:17]
	v_mfma_f32_32x32x16_bf16 v[34:49], v[184:187], v[252:255], v[34:49]
	s_waitcnt vmcnt(0)
	s_barrier
	ds_read_b128 v[92:95], v84 offset:32768
	ds_read_b128 v[96:99], v84 offset:36864
	ds_read_b128 v[100:103], v86 offset:32768
	ds_read_b128 v[144:147], v86 offset:36864
	ds_read_b128 v[148:151], v88 offset:32768
	ds_read_b128 v[152:155], v88 offset:36864
	ds_read_b128 v[180:183], v90 offset:32768
	ds_read_b128 v[184:187], v90 offset:36864
	s_waitcnt lgkmcnt(0)
	s_barrier
	v_mfma_f32_32x32x16_bf16 v[104:119], v[92:95], v[188:191], v[104:119]
	v_mfma_f32_32x32x16_bf16 v[128:143], v[92:95], v[192:195], v[128:143]
	v_mfma_f32_32x32x16_bf16 v[196:211], v[96:99], v[188:191], v[196:211]
	v_mfma_f32_32x32x16_bf16 v[236:251], v[96:99], v[192:195], v[236:251]
	v_mfma_f32_32x32x16_bf16 v[104:119], v[100:103], v[212:215], v[104:119]
	v_mfma_f32_32x32x16_bf16 v[128:143], v[100:103], v[216:219], v[128:143]
	v_mfma_f32_32x32x16_bf16 v[196:211], v[144:147], v[212:215], v[196:211]
	v_mfma_f32_32x32x16_bf16 v[236:251], v[144:147], v[216:219], v[236:251]
	v_mfma_f32_32x32x16_bf16 v[104:119], v[148:151], v[220:223], v[104:119]
	v_mfma_f32_32x32x16_bf16 v[128:143], v[148:151], v[224:227], v[128:143]
	v_mfma_f32_32x32x16_bf16 v[196:211], v[152:155], v[220:223], v[196:211]
	v_mfma_f32_32x32x16_bf16 v[236:251], v[152:155], v[224:227], v[236:251]
	v_mfma_f32_32x32x16_bf16 v[104:119], v[180:183], v[228:231], v[104:119]
	v_mfma_f32_32x32x16_bf16 v[128:143], v[180:183], v[252:255], v[128:143]
	v_mfma_f32_32x32x16_bf16 v[196:211], v[184:187], v[228:231], v[196:211]
	v_mfma_f32_32x32x16_bf16 v[236:251], v[184:187], v[252:255], v[236:251]
	s_waitcnt vmcnt(0) lgkmcnt(0)
	s_barrier

.Lg1o_loop:
	ds_read_b128 v[76:79], v68 offset:0
	ds_read_b128 v[80:83], v68 offset:4096
	ds_read_b128 v[148:151], v69 offset:0
	ds_read_b128 v[152:155], v69 offset:4096
	ds_read_b128 v[84:87], v70 offset:0
	ds_read_b128 v[88:91], v70 offset:4096
	ds_read_b128 v[180:183], v71 offset:0
	ds_read_b128 v[236:239], v71 offset:4096
	ds_read_b128 v[92:95], v72 offset:0
	ds_read_b128 v[96:99], v72 offset:4096
	ds_read_b128 v[240:243], v73 offset:0
	ds_read_b128 v[244:247], v73 offset:4096
	ds_read_b128 v[100:103], v74 offset:0
	ds_read_b128 v[144:147], v74 offset:4096
	ds_read_b128 v[248:251], v75 offset:0
	ds_read_b128 v[252:255], v75 offset:4096
	s_waitcnt lgkmcnt(0)
	s_barrier
	s_mov_b32 m0, s5
	v_mfma_f32_32x32x16_bf16 v[50:65], v[76:79], v[148:151], v[50:65]
	global_load_lds_dwordx4 v[104:105], off
	v_mfma_f32_32x32x16_bf16 v[34:49], v[76:79], v[152:155], v[34:49]
	s_add_i32 m0, s5, 0x400
	v_mfma_f32_32x32x16_bf16 v[18:33], v[80:83], v[148:151], v[18:33]
	global_load_lds_dwordx4 v[108:109], off
	v_mfma_f32_32x32x16_bf16 v[2:17], v[80:83], v[152:155], v[2:17]
	s_add_i32 m0, s5, 0x800
	v_mfma_f32_32x32x16_bf16 v[50:65], v[84:87], v[180:183], v[50:65]
	global_load_lds_dwordx4 v[112:113], off
	v_mfma_f32_32x32x16_bf16 v[34:49], v[84:87], v[236:239], v[34:49]
	s_add_i32 m0, s5, 0xc00
	v_mfma_f32_32x32x16_bf16 v[18:33], v[88:91], v[180:183], v[18:33]
	global_load_lds_dwordx4 v[116:117], off
	v_mfma_f32_32x32x16_bf16 v[2:17], v[88:91], v[236:239], v[2:17]
	s_mov_b32 m0, s15
	v_mfma_f32_32x32x16_bf16 v[50:65], v[92:95], v[240:243], v[50:65]
	global_load_lds_dwordx4 v[106:107], off
	v_lshl_add_u64 v[106:107], v[106:107], 0, s[34:35]
	v_mfma_f32_32x32x16_bf16 v[34:49], v[92:95], v[244:247], v[34:49]
	s_mov_b32 m0, s16
	v_mfma_f32_32x32x16_bf16 v[18:33], v[96:99], v[240:243], v[18:33]
	global_load_lds_dwordx4 v[110:111], off
	v_lshl_add_u64 v[110:111], v[110:111], 0, s[34:35]
	v_mfma_f32_32x32x16_bf16 v[2:17], v[96:99], v[244:247], v[2:17]
	v_mfma_f32_32x32x16_bf16 v[50:65], v[100:103], v[248:251], v[50:65]
	v_mfma_f32_32x32x16_bf16 v[34:49], v[100:103], v[252:255], v[34:49]
	v_mfma_f32_32x32x16_bf16 v[18:33], v[144:147], v[248:251], v[18:33]
	v_mfma_f32_32x32x16_bf16 v[2:17], v[144:147], v[252:255], v[2:17]
	s_waitcnt vmcnt(8)
	s_barrier
	ds_read_b128 v[76:79], v68 offset:32768
	ds_read_b128 v[80:83], v68 offset:36864
	ds_read_b128 v[84:87], v70 offset:32768
	ds_read_b128 v[88:91], v70 offset:36864
	ds_read_b128 v[92:95], v72 offset:32768
	ds_read_b128 v[96:99], v72 offset:36864
	ds_read_b128 v[100:103], v74 offset:32768
	ds_read_b128 v[144:147], v74 offset:36864
	s_waitcnt lgkmcnt(0)
	s_barrier
	s_add_i32 m0, s5, 0x8000
	v_lshl_add_u64 v[66:67], v[104:105], 0, s[8:9]
	v_mfma_f32_32x32x16_bf16 v[128:143], v[76:79], v[148:151], v[128:143]
	global_load_lds_dwordx4 v[66:67], off
	v_lshl_add_u64 v[104:105], v[104:105], 0, s[34:35]
	v_mfma_f32_32x32x16_bf16 v[184:199], v[76:79], v[152:155], v[184:199]
	s_add_i32 m0, s5, 0x8400
	v_lshl_add_u64 v[66:67], v[108:109], 0, s[8:9]
	v_mfma_f32_32x32x16_bf16 v[200:215], v[80:83], v[148:151], v[200:215]
	global_load_lds_dwordx4 v[66:67], off
	v_lshl_add_u64 v[108:109], v[108:109], 0, s[34:35]
	v_mfma_f32_32x32x16_bf16 v[216:231], v[80:83], v[152:155], v[216:231]
	s_add_i32 m0, s5, 0x8800
	v_lshl_add_u64 v[66:67], v[112:113], 0, s[8:9]
	v_mfma_f32_32x32x16_bf16 v[128:143], v[84:87], v[180:183], v[128:143]
	global_load_lds_dwordx4 v[66:67], off
	v_lshl_add_u64 v[112:113], v[112:113], 0, s[34:35]
	v_mfma_f32_32x32x16_bf16 v[184:199], v[84:87], v[236:239], v[184:199]
	s_add_i32 m0, s5, 0x8c00
	v_lshl_add_u64 v[66:67], v[116:117], 0, s[8:9]
	v_mfma_f32_32x32x16_bf16 v[200:215], v[88:91], v[180:183], v[200:215]
	global_load_lds_dwordx4 v[66:67], off
	v_lshl_add_u64 v[116:117], v[116:117], 0, s[34:35]
	v_mfma_f32_32x32x16_bf16 v[216:231], v[88:91], v[236:239], v[216:231]
	s_mov_b32 m0, s17
	v_mfma_f32_32x32x16_bf16 v[128:143], v[92:95], v[240:243], v[128:143]
	global_load_lds_dwordx4 v[114:115], off
	v_lshl_add_u64 v[114:115], v[114:115], 0, s[34:35]
	v_mfma_f32_32x32x16_bf16 v[184:199], v[92:95], v[244:247], v[184:199]
	s_mov_b32 m0, s22
	v_mfma_f32_32x32x16_bf16 v[200:215], v[96:99], v[240:243], v[200:215]
	global_load_lds_dwordx4 v[118:119], off
	v_lshl_add_u64 v[118:119], v[118:119], 0, s[34:35]
	v_mfma_f32_32x32x16_bf16 v[216:231], v[96:99], v[244:247], v[216:231]
	v_mfma_f32_32x32x16_bf16 v[128:143], v[100:103], v[248:251], v[128:143]
	v_mfma_f32_32x32x16_bf16 v[184:199], v[100:103], v[252:255], v[184:199]
	v_mfma_f32_32x32x16_bf16 v[200:215], v[144:147], v[248:251], v[200:215]
	v_mfma_f32_32x32x16_bf16 v[216:231], v[144:147], v[252:255], v[216:231]
	s_waitcnt vmcnt(8)
	s_barrier
	ds_read_b128 v[76:79], v68 offset:0
	ds_read_b128 v[80:83], v68 offset:4096
	ds_read_b128 v[148:151], v69 offset:32768
	ds_read_b128 v[152:155], v69 offset:36864
	ds_read_b128 v[84:87], v70 offset:0
	ds_read_b128 v[88:91], v70 offset:4096
	ds_read_b128 v[180:183], v71 offset:32768
	ds_read_b128 v[236:239], v71 offset:36864
	ds_read_b128 v[92:95], v72 offset:0
	ds_read_b128 v[96:99], v72 offset:4096
	ds_read_b128 v[240:243], v73 offset:32768
	ds_read_b128 v[244:247], v73 offset:36864
	ds_read_b128 v[100:103], v74 offset:0
	ds_read_b128 v[144:147], v74 offset:4096
	ds_read_b128 v[248:251], v75 offset:32768
	ds_read_b128 v[252:255], v75 offset:36864
	s_waitcnt lgkmcnt(0)
	s_barrier
	s_mov_b32 m0, s5
	v_mfma_f32_32x32x16_bf16 v[50:65], v[76:79], v[148:151], v[50:65]
	global_load_lds_dwordx4 v[104:105], off
	v_mfma_f32_32x32x16_bf16 v[34:49], v[76:79], v[152:155], v[34:49]
	s_add_i32 m0, s5, 0x400
	v_mfma_f32_32x32x16_bf16 v[18:33], v[80:83], v[148:151], v[18:33]
	global_load_lds_dwordx4 v[108:109], off
	v_mfma_f32_32x32x16_bf16 v[2:17], v[80:83], v[152:155], v[2:17]
	s_add_i32 m0, s5, 0x800
	v_mfma_f32_32x32x16_bf16 v[50:65], v[84:87], v[180:183], v[50:65]
	global_load_lds_dwordx4 v[112:113], off
	v_mfma_f32_32x32x16_bf16 v[34:49], v[84:87], v[236:239], v[34:49]
	s_add_i32 m0, s5, 0xc00
	v_mfma_f32_32x32x16_bf16 v[18:33], v[88:91], v[180:183], v[18:33]
	global_load_lds_dwordx4 v[116:117], off
	v_mfma_f32_32x32x16_bf16 v[2:17], v[88:91], v[236:239], v[2:17]
	s_add_i32 m0, s5, 0xc000
	v_mfma_f32_32x32x16_bf16 v[50:65], v[92:95], v[240:243], v[50:65]
	global_load_lds_dwordx4 v[106:107], off
	v_lshl_add_u64 v[106:107], v[106:107], 0, s[34:35]
	v_mfma_f32_32x32x16_bf16 v[34:49], v[92:95], v[244:247], v[34:49]
	s_add_i32 m0, s5, 0xc400
	v_mfma_f32_32x32x16_bf16 v[18:33], v[96:99], v[240:243], v[18:33]
	global_load_lds_dwordx4 v[110:111], off
	v_lshl_add_u64 v[110:111], v[110:111], 0, s[34:35]
	v_mfma_f32_32x32x16_bf16 v[2:17], v[96:99], v[244:247], v[2:17]
	v_mfma_f32_32x32x16_bf16 v[50:65], v[100:103], v[248:251], v[50:65]
	v_mfma_f32_32x32x16_bf16 v[34:49], v[100:103], v[252:255], v[34:49]
	v_mfma_f32_32x32x16_bf16 v[18:33], v[144:147], v[248:251], v[18:33]
	v_mfma_f32_32x32x16_bf16 v[2:17], v[144:147], v[252:255], v[2:17]
	s_waitcnt vmcnt(8)
	s_barrier
	ds_read_b128 v[76:79], v68 offset:32768
	ds_read_b128 v[80:83], v68 offset:36864
	ds_read_b128 v[84:87], v70 offset:32768
	ds_read_b128 v[88:91], v70 offset:36864
	ds_read_b128 v[92:95], v72 offset:32768
	ds_read_b128 v[96:99], v72 offset:36864
	ds_read_b128 v[100:103], v74 offset:32768
	ds_read_b128 v[144:147], v74 offset:36864
	s_waitcnt lgkmcnt(0)
	s_barrier
	s_add_i32 m0, s5, 0x8000
	v_lshl_add_u64 v[66:67], v[104:105], 0, s[8:9]
	v_mfma_f32_32x32x16_bf16 v[128:143], v[76:79], v[148:151], v[128:143]
	global_load_lds_dwordx4 v[66:67], off
	v_lshl_add_u64 v[104:105], v[104:105], 0, s[34:35]
	v_mfma_f32_32x32x16_bf16 v[184:199], v[76:79], v[152:155], v[184:199]
	s_add_i32 m0, s5, 0x8400
	v_lshl_add_u64 v[66:67], v[108:109], 0, s[8:9]
	v_mfma_f32_32x32x16_bf16 v[200:215], v[80:83], v[148:151], v[200:215]
	global_load_lds_dwordx4 v[66:67], off
	v_lshl_add_u64 v[108:109], v[108:109], 0, s[34:35]
	v_mfma_f32_32x32x16_bf16 v[216:231], v[80:83], v[152:155], v[216:231]
	s_add_i32 m0, s5, 0x8800
	v_lshl_add_u64 v[66:67], v[112:113], 0, s[8:9]
	v_mfma_f32_32x32x16_bf16 v[128:143], v[84:87], v[180:183], v[128:143]
	global_load_lds_dwordx4 v[66:67], off
	v_lshl_add_u64 v[112:113], v[112:113], 0, s[34:35]
	v_mfma_f32_32x32x16_bf16 v[184:199], v[84:87], v[236:239], v[184:199]
	s_add_i32 m0, s5, 0x8c00
	v_lshl_add_u64 v[66:67], v[116:117], 0, s[8:9]
	v_mfma_f32_32x32x16_bf16 v[200:215], v[88:91], v[180:183], v[200:215]
	global_load_lds_dwordx4 v[66:67], off
	v_lshl_add_u64 v[116:117], v[116:117], 0, s[34:35]
	v_mfma_f32_32x32x16_bf16 v[216:231], v[88:91], v[236:239], v[216:231]
	s_add_i32 m0, s5, 0xc800
	v_mfma_f32_32x32x16_bf16 v[128:143], v[92:95], v[240:243], v[128:143]
	global_load_lds_dwordx4 v[114:115], off
	v_lshl_add_u64 v[114:115], v[114:115], 0, s[34:35]
	v_mfma_f32_32x32x16_bf16 v[184:199], v[92:95], v[244:247], v[184:199]
	s_add_i32 m0, s5, 0xcc00
	v_mfma_f32_32x32x16_bf16 v[200:215], v[96:99], v[240:243], v[200:215]
	global_load_lds_dwordx4 v[118:119], off
	v_lshl_add_u64 v[118:119], v[118:119], 0, s[34:35]
	v_mfma_f32_32x32x16_bf16 v[216:231], v[96:99], v[244:247], v[216:231]
	v_mfma_f32_32x32x16_bf16 v[128:143], v[100:103], v[248:251], v[128:143]
	v_mfma_f32_32x32x16_bf16 v[184:199], v[100:103], v[252:255], v[184:199]
	v_mfma_f32_32x32x16_bf16 v[200:215], v[144:147], v[248:251], v[200:215]
	v_mfma_f32_32x32x16_bf16 v[216:231], v[144:147], v[252:255], v[216:231]
	s_waitcnt vmcnt(8)
	s_barrier
	s_add_i32 s23, s23, 2
	s_cmp_lt_u32 s23, 14
	s_cbranch_scc1 .Lg1o_loop
	ds_read_b128 v[76:79], v68 offset:0
	ds_read_b128 v[80:83], v68 offset:4096
	ds_read_b128 v[148:151], v69 offset:0
	ds_read_b128 v[152:155], v69 offset:4096
	ds_read_b128 v[84:87], v70 offset:0
	ds_read_b128 v[88:91], v70 offset:4096
	ds_read_b128 v[180:183], v71 offset:0
	ds_read_b128 v[236:239], v71 offset:4096
	ds_read_b128 v[92:95], v72 offset:0
	ds_read_b128 v[96:99], v72 offset:4096
	ds_read_b128 v[240:243], v73 offset:0
	ds_read_b128 v[244:247], v73 offset:4096
	ds_read_b128 v[100:103], v74 offset:0
	ds_read_b128 v[144:147], v74 offset:4096
	ds_read_b128 v[248:251], v75 offset:0
	ds_read_b128 v[252:255], v75 offset:4096
	s_waitcnt lgkmcnt(0)
	s_barrier
	s_mov_b32 m0, s5
	v_mfma_f32_32x32x16_bf16 v[50:65], v[76:79], v[148:151], v[50:65]
	global_load_lds_dwordx4 v[104:105], off
	v_mfma_f32_32x32x16_bf16 v[34:49], v[76:79], v[152:155], v[34:49]
	s_add_i32 m0, s5, 0x400
	v_mfma_f32_32x32x16_bf16 v[18:33], v[80:83], v[148:151], v[18:33]
	global_load_lds_dwordx4 v[108:109], off
	v_mfma_f32_32x32x16_bf16 v[2:17], v[80:83], v[152:155], v[2:17]
	s_add_i32 m0, s5, 0x800
	v_mfma_f32_32x32x16_bf16 v[50:65], v[84:87], v[180:183], v[50:65]
	global_load_lds_dwordx4 v[112:113], off
	v_mfma_f32_32x32x16_bf16 v[34:49], v[84:87], v[236:239], v[34:49]
	s_add_i32 m0, s5, 0xc00
	v_mfma_f32_32x32x16_bf16 v[18:33], v[88:91], v[180:183], v[18:33]
	global_load_lds_dwordx4 v[116:117], off
	v_mfma_f32_32x32x16_bf16 v[2:17], v[88:91], v[236:239], v[2:17]
	v_mfma_f32_32x32x16_bf16 v[50:65], v[92:95], v[240:243], v[50:65]
	v_mfma_f32_32x32x16_bf16 v[34:49], v[92:95], v[244:247], v[34:49]
	v_mfma_f32_32x32x16_bf16 v[18:33], v[96:99], v[240:243], v[18:33]
	v_mfma_f32_32x32x16_bf16 v[2:17], v[96:99], v[244:247], v[2:17]
	v_mfma_f32_32x32x16_bf16 v[50:65], v[100:103], v[248:251], v[50:65]
	v_mfma_f32_32x32x16_bf16 v[34:49], v[100:103], v[252:255], v[34:49]
	v_mfma_f32_32x32x16_bf16 v[18:33], v[144:147], v[248:251], v[18:33]
	v_mfma_f32_32x32x16_bf16 v[2:17], v[144:147], v[252:255], v[2:17]
	s_waitcnt vmcnt(4)
	s_barrier
	ds_read_b128 v[76:79], v68 offset:32768
	ds_read_b128 v[80:83], v68 offset:36864
	ds_read_b128 v[84:87], v70 offset:32768
	ds_read_b128 v[88:91], v70 offset:36864
	ds_read_b128 v[92:95], v72 offset:32768
	ds_read_b128 v[96:99], v72 offset:36864
	ds_read_b128 v[100:103], v74 offset:32768
	ds_read_b128 v[144:147], v74 offset:36864
	s_waitcnt lgkmcnt(0)
	s_barrier
	s_add_i32 m0, s5, 0x8000
	v_lshl_add_u64 v[66:67], v[104:105], 0, s[8:9]
	v_mfma_f32_32x32x16_bf16 v[128:143], v[76:79], v[148:151], v[128:143]
	global_load_lds_dwordx4 v[66:67], off
	v_lshl_add_u64 v[104:105], v[104:105], 0, s[34:35]
	v_mfma_f32_32x32x16_bf16 v[184:199], v[76:79], v[152:155], v[184:199]
	s_add_i32 m0, s5, 0x8400
	v_lshl_add_u64 v[66:67], v[108:109], 0, s[8:9]
	v_mfma_f32_32x32x16_bf16 v[200:215], v[80:83], v[148:151], v[200:215]
	global_load_lds_dwordx4 v[66:67], off
	v_lshl_add_u64 v[108:109], v[108:109], 0, s[34:35]
	v_mfma_f32_32x32x16_bf16 v[216:231], v[80:83], v[152:155], v[216:231]
	s_add_i32 m0, s5, 0x8800
	v_lshl_add_u64 v[66:67], v[112:113], 0, s[8:9]
	v_mfma_f32_32x32x16_bf16 v[128:143], v[84:87], v[180:183], v[128:143]
	global_load_lds_dwordx4 v[66:67], off
	v_lshl_add_u64 v[112:113], v[112:113], 0, s[34:35]
	v_mfma_f32_32x32x16_bf16 v[184:199], v[84:87], v[236:239], v[184:199]
	s_add_i32 m0, s5, 0x8c00
	v_lshl_add_u64 v[66:67], v[116:117], 0, s[8:9]
	v_mfma_f32_32x32x16_bf16 v[200:215], v[88:91], v[180:183], v[200:215]
	global_load_lds_dwordx4 v[66:67], off
	v_lshl_add_u64 v[116:117], v[116:117], 0, s[34:35]
	v_mfma_f32_32x32x16_bf16 v[216:231], v[88:91], v[236:239], v[216:231]
	v_mfma_f32_32x32x16_bf16 v[128:143], v[92:95], v[240:243], v[128:143]
	v_mfma_f32_32x32x16_bf16 v[184:199], v[92:95], v[244:247], v[184:199]
	v_mfma_f32_32x32x16_bf16 v[200:215], v[96:99], v[240:243], v[200:215]
	v_mfma_f32_32x32x16_bf16 v[216:231], v[96:99], v[244:247], v[216:231]
	v_mfma_f32_32x32x16_bf16 v[128:143], v[100:103], v[248:251], v[128:143]
	v_mfma_f32_32x32x16_bf16 v[184:199], v[100:103], v[252:255], v[184:199]
	v_mfma_f32_32x32x16_bf16 v[200:215], v[144:147], v[248:251], v[200:215]
	v_mfma_f32_32x32x16_bf16 v[216:231], v[144:147], v[252:255], v[216:231]
	s_waitcnt vmcnt(4)
	s_barrier
	ds_read_b128 v[76:79], v68 offset:0
	ds_read_b128 v[80:83], v68 offset:4096
	ds_read_b128 v[148:151], v69 offset:32768
	ds_read_b128 v[152:155], v69 offset:36864
	ds_read_b128 v[84:87], v70 offset:0
	ds_read_b128 v[88:91], v70 offset:4096
	ds_read_b128 v[180:183], v71 offset:32768
	ds_read_b128 v[236:239], v71 offset:36864
	ds_read_b128 v[92:95], v72 offset:0
	ds_read_b128 v[96:99], v72 offset:4096
	ds_read_b128 v[240:243], v73 offset:32768
	ds_read_b128 v[244:247], v73 offset:36864
	ds_read_b128 v[100:103], v74 offset:0
	ds_read_b128 v[144:147], v74 offset:4096
	ds_read_b128 v[248:251], v75 offset:32768
	ds_read_b128 v[252:255], v75 offset:36864
	s_waitcnt lgkmcnt(0)
	s_barrier
	v_mfma_f32_32x32x16_bf16 v[50:65], v[76:79], v[148:151], v[50:65]
	v_mfma_f32_32x32x16_bf16 v[34:49], v[76:79], v[152:155], v[34:49]
	v_mfma_f32_32x32x16_bf16 v[18:33], v[80:83], v[148:151], v[18:33]
	v_mfma_f32_32x32x16_bf16 v[2:17], v[80:83], v[152:155], v[2:17]
	v_mfma_f32_32x32x16_bf16 v[50:65], v[84:87], v[180:183], v[50:65]
	v_mfma_f32_32x32x16_bf16 v[34:49], v[84:87], v[236:239], v[34:49]
	v_mfma_f32_32x32x16_bf16 v[18:33], v[88:91], v[180:183], v[18:33]
	v_mfma_f32_32x32x16_bf16 v[2:17], v[88:91], v[236:239], v[2:17]
	v_mfma_f32_32x32x16_bf16 v[50:65], v[92:95], v[240:243], v[50:65]
	v_mfma_f32_32x32x16_bf16 v[34:49], v[92:95], v[244:247], v[34:49]
	v_mfma_f32_32x32x16_bf16 v[18:33], v[96:99], v[240:243], v[18:33]
	v_mfma_f32_32x32x16_bf16 v[2:17], v[96:99], v[244:247], v[2:17]
	v_mfma_f32_32x32x16_bf16 v[50:65], v[100:103], v[248:251], v[50:65]
	v_mfma_f32_32x32x16_bf16 v[34:49], v[100:103], v[252:255], v[34:49]
	v_mfma_f32_32x32x16_bf16 v[18:33], v[144:147], v[248:251], v[18:33]
	v_mfma_f32_32x32x16_bf16 v[2:17], v[144:147], v[252:255], v[2:17]
	s_waitcnt vmcnt(0)
	s_barrier
	ds_read_b128 v[76:79], v68 offset:32768
	ds_read_b128 v[80:83], v68 offset:36864
	ds_read_b128 v[84:87], v70 offset:32768
	ds_read_b128 v[88:91], v70 offset:36864
	ds_read_b128 v[92:95], v72 offset:32768
	ds_read_b128 v[96:99], v72 offset:36864
	ds_read_b128 v[100:103], v74 offset:32768
	ds_read_b128 v[144:147], v74 offset:36864
	s_waitcnt lgkmcnt(0)
	s_barrier
	v_mfma_f32_32x32x16_bf16 v[128:143], v[76:79], v[148:151], v[128:143]
	v_mfma_f32_32x32x16_bf16 v[184:199], v[76:79], v[152:155], v[184:199]
	v_mfma_f32_32x32x16_bf16 v[200:215], v[80:83], v[148:151], v[200:215]
	v_mfma_f32_32x32x16_bf16 v[216:231], v[80:83], v[152:155], v[216:231]
	v_mfma_f32_32x32x16_bf16 v[128:143], v[84:87], v[180:183], v[128:143]
	v_mfma_f32_32x32x16_bf16 v[184:199], v[84:87], v[236:239], v[184:199]
	v_mfma_f32_32x32x16_bf16 v[200:215], v[88:91], v[180:183], v[200:215]
	v_mfma_f32_32x32x16_bf16 v[216:231], v[88:91], v[236:239], v[216:231]
	v_mfma_f32_32x32x16_bf16 v[128:143], v[92:95], v[240:243], v[128:143]
	v_mfma_f32_32x32x16_bf16 v[184:199], v[92:95], v[244:247], v[184:199]
	v_mfma_f32_32x32x16_bf16 v[200:215], v[96:99], v[240:243], v[200:215]
	v_mfma_f32_32x32x16_bf16 v[216:231], v[96:99], v[244:247], v[216:231]
	v_mfma_f32_32x32x16_bf16 v[128:143], v[100:103], v[248:251], v[128:143]
	v_mfma_f32_32x32x16_bf16 v[184:199], v[100:103], v[252:255], v[184:199]
	v_mfma_f32_32x32x16_bf16 v[200:215], v[144:147], v[248:251], v[200:215]
	v_mfma_f32_32x32x16_bf16 v[216:231], v[144:147], v[252:255], v[216:231]
	s_waitcnt vmcnt(0) lgkmcnt(0)
	s_barrier
	v_readlane_b32 s8, v232, 16
	v_readlane_b32 s9, v232, 17
	v_readlane_b32 s10, v234, 2
	v_readlane_b32 s11, v234, 3
	s_nop 3
	s_and_b64 s[8:9], s[8:9], exec
	s_cselect_b32 s9, s11, s79
	s_cselect_b32 s8, s10, s78
	v_and_b32_e32 v104, 15, v156
	v_lshlrev_b32_e32 v104, 4, v104
	v_bfe_u32 v105, v156, 4, 2
	v_lshrrev_b32_e32 v106, 6, v156
	v_lshlrev_b32_e32 v106, 14, v106
	v_or_b32_e32 v107, v106, v104
	v_lshrrev_b32_e32 v66, 1, v156
	v_and_b32_e32 v66, 0xffffffc0, v66
	v_lshlrev_b32_e32 v66, 10, v66
	v_and_b32_e32 v108, 64, v156
	v_or_b32_e32 v66, v66, v108
	v_mov_b32_e32 v67, 0
	v_lshlrev_b32_e32 v108, 12, v105
	v_add_u32_e32 v110, v104, v108
	v_mov_b32_e32 v111, 0
	v_lshl_add_u64 v[68:69], s[8:9], 0, v[110:111]
	v_and_b32_e32 v109, 31, v156
	v_lshlrev_b32_e32 v109, 2, v109
	v_bfe_u32 v112, v156, 5, 1
	v_lshlrev_b32_e32 v112, 10, v112
	v_or3_b32 v125, v106, v109, v112
	v_mov_b32_e32 v70, v108
	v_mov_b32_e32 v72, v104
	v_add_u32_e32 v74, 0x4000, v108
	v_add_u32_e32 v76, 0x8000, v108
	v_add_u32_e32 v78, 0xc000, v108
	v_add_u32_e32 v80, 0x10000, v108
	v_add_u32_e32 v82, 0x14000, v108
	v_add_u32_e32 v84, 0x18000, v108
	v_add_u32_e32 v86, 0x1c000, v108
	v_add_u32_e32 v88, 0x20000, v108
	v_add_u32_e32 v90, 0x24000, v108
	v_add_u32_e32 v92, 0x28000, v108
	v_add_u32_e32 v94, 0x2c000, v108
	v_add_u32_e32 v96, 0x30000, v108
	v_add_u32_e32 v98, 0x34000, v108
	v_add_u32_e32 v100, 0x38000, v108
	v_add_u32_e32 v102, 0x3c000, v108
	v_lshl_add_u32 v109, v105, 8, v107
	v_mov_b32_e32 v144, v109
	v_add_u32_e32 v145, 0x400, v109
	v_add_u32_e32 v146, 0x800, v109
	v_add_u32_e32 v147, 0xc00, v109
	v_add_u32_e32 v148, 0x1000, v109
	v_add_u32_e32 v149, 0x1400, v109
	v_add_u32_e32 v150, 0x1800, v109
	v_add_u32_e32 v151, 0x1c00, v109
	v_add_u32_e32 v152, 0x2000, v109
	v_add_u32_e32 v153, 0x2400, v109
	v_add_u32_e32 v154, 0x2800, v109
	v_add_u32_e32 v155, 0x2c00, v109
	v_add_u32_e32 v180, 0x3000, v109
	v_add_u32_e32 v181, 0x3400, v109
	v_add_u32_e32 v182, 0x3800, v109
	v_add_u32_e32 v183, 0x3c00, v109
	s_branch .LBB0_993
